# RWKV scan body: per-step output partial add in its 8-byte encoding so most 8-byte instructions of the issue-bound scan stream sit 8-byte aligned
# baseline (speedup 1.0000x reference)
; #define LAS __attribute__((address_space(3)))
; __device__ __forceinline__ float row16_sum(float v) { v += dpp_f<0xB1>(v); v += dpp_f<0x4E>(v); v += dpp_f<0x141>(v); v += dpp_f<0x140>(v); return v; }
; __device__ __forceinline__ void rwkv_scan_unit(LAS unsigned char* lds, const float* Wd, const float* V, const bf16_t* RKKB, float* Yraw, int p, int rg, int tid) {
;     ...
;     for (int c = 0; c < NCH; ++c) {
;         if (wave >= 4) { if (c + 2 < NCH) scan_load_chunk(lds + ((c + 2) % 3) * SCAN_SLOT_B, Wd, V, RKKB, p, rg, (c + 2) * SCAN_CH, tid - 256); }
;         else {
;             LAS const unsigned char* sl = lds + (c % 3) * SCAN_SLOT_B + kq * 16;
;             LAS const unsigned char* vl = lds + (c % 3) * SCAN_SLOT_B + 1280 + rl * 4;
;             float* yo = Yraw + ((size_t)p * SEQ + c * SCAN_CH + kq) * 64 + rg * 16 + rl;
;             f32x4 w = *(LAS const f32x4*)(sl), b = *(LAS const f32x4*)(sl + 256), k = *(LAS const f32x4*)(sl + 512), kk = *(LAS const f32x4*)(sl + 768), r = *(LAS const f32x4*)(sl + 1024);
;             float v = *(LAS const float*)(vl); float yp[16];
; #pragma unroll
;             for (int st = 0; st < SCAN_CH; ++st) {
;                 f32x4 wn = w, bn = b, kn = k, kkn = kk, rn = r; float vn = v;
;                 if (st + 1 < SCAN_CH) { const int o = (st + 1) * SCAN_STEP_B;
;                     wn = *(LAS const f32x4*)(sl + o); bn = *(LAS const f32x4*)(sl + o + 256); kn = *(LAS const f32x4*)(sl + o + 512); kkn = *(LAS const f32x4*)(sl + o + 768); rn = *(LAS const f32x4*)(sl + o + 1024);
;                     vn = *(LAS const float*)(vl + o); }
;                 float sa = (S[0] * kk[0] + S[1] * kk[1]) + (S[2] * kk[2] + S[3] * kk[3]);
;                 const f32x4 kvt = k * v;
;                 sa = -row16_sum(sa);
;                 S = S * w + (b * sa + kvt);
;                 yp[st & 15] = (S[0] * r[0] + S[1] * r[1]) + (S[2] * r[2] + S[3] * r[3]);
;                 if ((st & 15) == 15) yo[(size_t)(st - 15) * 64] = tr16_sum(yp, kq);
;                 w = wn; b = bn; k = kn; kk = kkn; r = rn; v = vn;
;             }
.Lscan_top:
	s_mul_i32 s18, s22, 0xab
	s_bfe_u32 s18, s18, 0x70009
	s_mul_i32 s18, s18, 3
	s_sub_i32 s18, s22, s18
	s_and_b32 s18, s18, 0xff
	s_mul_i32 s18, s18, 0xa800
	s_add_i32 s19, s18, 0xa800
	s_cmp_eq_u32 s19, 0x1f800
	s_cselect_b32 s19, 0, s19
	v_add_u32_e32 v84, s18, v71
	v_add_u32_e32 v83, s18, v72
	v_add_u32_e32 v86, s19, v71
	v_add_u32_e32 v85, s19, v72
	v_lshl_add_u64 v[62:63], v[60:61], 0, s[14:15]
	s_mov_b64 s[20:21], 0x16100000
	v_lshl_add_u64 v[88:89], v[62:63], 0, s[20:21]
	s_mov_b64 s[20:21], 0x16101000
	v_lshl_add_u64 v[90:91], v[62:63], 0, s[20:21]
	s_lshr_b32 s20, s18, 15
	s_lshl_b32 s20, s20, 11
	s_add_i32 s20, s20, 0x1f800
	v_lshl_add_u32 v96, v72, 5, s20
	s_lshr_b32 s21, s19, 15
	s_lshl_b32 s21, s21, 11
	s_add_i32 s21, s21, 0x1f800
	v_lshl_add_u32 v97, v72, 5, s21
	s_waitcnt lgkmcnt(5)
	v_pk_mul_f32 v[10:11], v[2:3], v[132:133]
	v_pk_fma_f32 v[10:11], v[4:5], v[134:135], v[10:11]
	v_pk_mul_f32 v[6:7], v[128:129], v[116:117] op_sel_hi:[1,0]
	v_add_f32_e32 v12, v10, v11
	v_pk_mul_f32 v[8:9], v[130:131], v[116:117] op_sel_hi:[1,0]
	v_pk_fma_f32 v[6:7], v[2:3], v[120:121], v[6:7]
	v_add_f32_dpp v12, v12, v12 quad_perm:[1,0,3,2] row_mask:0xf bank_mask:0xf bound_ctrl:1
	v_pk_fma_f32 v[8:9], v[4:5], v[122:123], v[8:9]
	ds_read_b128 v[180:183], v84 offset:3456
	v_add_f32_dpp v12, v12, v12 quad_perm:[2,3,0,1] row_mask:0xf bank_mask:0xf bound_ctrl:1
	ds_read_b128 v[168:171], v84 offset:2688
	ds_read_b128 v[176:179], v84 offset:3200
	v_add_f32_dpp v12, v12, v12 row_half_mirror row_mask:0xf bank_mask:0xf bound_ctrl:1
	ds_read_b128 v[172:175], v84 offset:2944
	ds_read_b128 v[184:187], v84 offset:3712
	v_add_f32_dpp v12, v12, v12 row_mirror row_mask:0xf bank_mask:0xf bound_ctrl:1
	v_pk_fma_f32 v[2:3], v[124:125], v[12:13], v[6:7] op_sel_hi:[1,0,1] neg_lo:[0,1,0] neg_hi:[0,1,0]
	v_pk_fma_f32 v[4:5], v[126:127], v[12:13], v[8:9] op_sel_hi:[1,0,1] neg_lo:[0,1,0] neg_hi:[0,1,0]
	s_waitcnt lgkmcnt(5)
	v_pk_mul_f32 v[10:11], v[2:3], v[156:157]
	v_pk_fma_f32 v[10:11], v[4:5], v[158:159], v[10:11]
	v_pk_mul_f32 v[14:15], v[2:3], v[136:137]
	v_add_f32_e32 v12, v10, v11
	v_pk_fma_f32 v[14:15], v[4:5], v[138:139], v[14:15]
	v_add_f32_e64 v100, v14, v15
	v_add_f32_dpp v12, v12, v12 quad_perm:[1,0,3,2] row_mask:0xf bank_mask:0xf bound_ctrl:1
	v_pk_mul_f32 v[6:7], v[152:153], v[116:117] op_sel:[0,1] op_sel_hi:[1,1]
	v_pk_mul_f32 v[8:9], v[154:155], v[116:117] op_sel:[0,1] op_sel_hi:[1,1]
	v_add_f32_dpp v12, v12, v12 quad_perm:[2,3,0,1] row_mask:0xf bank_mask:0xf bound_ctrl:1
	v_pk_fma_f32 v[6:7], v[2:3], v[144:145], v[6:7]
	v_pk_fma_f32 v[8:9], v[4:5], v[146:147], v[8:9]
	v_add_f32_dpp v12, v12, v12 row_half_mirror row_mask:0xf bank_mask:0xf bound_ctrl:1
	ds_read_b128 v[34:37], v84 offset:4800
	ds_read_b128 v[22:25], v84 offset:4032
	v_add_f32_dpp v12, v12, v12 row_mirror row_mask:0xf bank_mask:0xf bound_ctrl:1
	ds_read_b128 v[30:33], v84 offset:4544
	ds_read_b128 v[26:29], v84 offset:4288
	ds_read_b128 v[38:41], v84 offset:5056
	v_pk_fma_f32 v[2:3], v[148:149], v[12:13], v[6:7] op_sel_hi:[1,0,1] neg_lo:[0,1,0] neg_hi:[0,1,0]
	v_pk_fma_f32 v[4:5], v[150:151], v[12:13], v[8:9] op_sel_hi:[1,0,1] neg_lo:[0,1,0] neg_hi:[0,1,0]
	s_waitcnt lgkmcnt(5)
	v_pk_mul_f32 v[10:11], v[2:3], v[180:181]
	v_pk_fma_f32 v[10:11], v[4:5], v[182:183], v[10:11]
	v_pk_mul_f32 v[14:15], v[2:3], v[160:161]
	v_add_f32_e32 v12, v10, v11
	v_pk_fma_f32 v[14:15], v[4:5], v[162:163], v[14:15]
	v_add_f32_e64 v101, v14, v15
	v_add_f32_dpp v12, v12, v12 quad_perm:[1,0,3,2] row_mask:0xf bank_mask:0xf bound_ctrl:1
	v_pk_mul_f32 v[6:7], v[176:177], v[118:119] op_sel_hi:[1,0]
	v_pk_mul_f32 v[8:9], v[178:179], v[118:119] op_sel_hi:[1,0]
	v_add_f32_dpp v12, v12, v12 quad_perm:[2,3,0,1] row_mask:0xf bank_mask:0xf bound_ctrl:1
	v_pk_fma_f32 v[6:7], v[2:3], v[168:169], v[6:7]
	v_pk_fma_f32 v[8:9], v[4:5], v[170:171], v[8:9]
	v_add_f32_dpp v12, v12, v12 row_half_mirror row_mask:0xf bank_mask:0xf bound_ctrl:1
	ds_read_b128 v[132:135], v84 offset:6144
	ds_read_b128 v[120:123], v84 offset:5376
	v_add_f32_dpp v12, v12, v12 row_mirror row_mask:0xf bank_mask:0xf bound_ctrl:1
	ds_read_b128 v[128:131], v84 offset:5888
	ds_read_b128 v[92:95], v96 offset:16
	ds_read_b128 v[124:127], v84 offset:5632
	ds_read_b128 v[136:139], v84 offset:6400
	v_pk_fma_f32 v[2:3], v[172:173], v[12:13], v[6:7] op_sel_hi:[1,0,1] neg_lo:[0,1,0] neg_hi:[0,1,0]
	v_pk_fma_f32 v[4:5], v[174:175], v[12:13], v[8:9] op_sel_hi:[1,0,1] neg_lo:[0,1,0] neg_hi:[0,1,0]
	s_waitcnt lgkmcnt(6)
	v_pk_mul_f32 v[10:11], v[2:3], v[34:35]
	v_pk_fma_f32 v[10:11], v[4:5], v[36:37], v[10:11]
	v_pk_mul_f32 v[14:15], v[2:3], v[184:185]
	v_add_f32_e32 v12, v10, v11
	v_pk_fma_f32 v[14:15], v[4:5], v[186:187], v[14:15]
	v_add_f32_e64 v102, v14, v15
	v_add_f32_dpp v12, v12, v12 quad_perm:[1,0,3,2] row_mask:0xf bank_mask:0xf bound_ctrl:1
	v_pk_mul_f32 v[6:7], v[30:31], v[118:119] op_sel:[0,1] op_sel_hi:[1,1]
	v_pk_mul_f32 v[8:9], v[32:33], v[118:119] op_sel:[0,1] op_sel_hi:[1,1]
	v_add_f32_dpp v12, v12, v12 quad_perm:[2,3,0,1] row_mask:0xf bank_mask:0xf bound_ctrl:1
	v_pk_fma_f32 v[6:7], v[2:3], v[22:23], v[6:7]
	v_pk_fma_f32 v[8:9], v[4:5], v[24:25], v[8:9]
	v_add_f32_dpp v12, v12, v12 row_half_mirror row_mask:0xf bank_mask:0xf bound_ctrl:1
	ds_read_b128 v[156:159], v84 offset:7488
	ds_read_b128 v[144:147], v84 offset:6720
	v_add_f32_dpp v12, v12, v12 row_mirror row_mask:0xf bank_mask:0xf bound_ctrl:1
	ds_read_b128 v[152:155], v84 offset:7232
	ds_read_b128 v[148:151], v84 offset:6976
	ds_read_b128 v[160:163], v84 offset:7744
	v_pk_fma_f32 v[2:3], v[26:27], v[12:13], v[6:7] op_sel_hi:[1,0,1] neg_lo:[0,1,0] neg_hi:[0,1,0]
	v_pk_fma_f32 v[4:5], v[28:29], v[12:13], v[8:9] op_sel_hi:[1,0,1] neg_lo:[0,1,0] neg_hi:[0,1,0]
	s_waitcnt lgkmcnt(5)
; #define LAS __attribute__((address_space(3)))
; __device__ __forceinline__ float row16_sum(float v) { v += dpp_f<0xB1>(v); v += dpp_f<0x4E>(v); v += dpp_f<0x141>(v); v += dpp_f<0x140>(v); return v; }
; __device__ __forceinline__ void rwkv_scan_unit(LAS unsigned char* lds, const float* Wd, const float* V, const bf16_t* RKKB, float* Yraw, int p, int rg, int tid) {
;     ...
;             for (int st = 0; st < SCAN_CH; ++st) {
;                 f32x4 wn = w, bn = b, kn = k, kkn = kk, rn = r; float vn = v;
;                 if (st + 1 < SCAN_CH) { const int o = (st + 1) * SCAN_STEP_B;
;                     wn = *(LAS const f32x4*)(sl + o); bn = *(LAS const f32x4*)(sl + o + 256); kn = *(LAS const f32x4*)(sl + o + 512); kkn = *(LAS const f32x4*)(sl + o + 768); rn = *(LAS const f32x4*)(sl + o + 1024);
;                     vn = *(LAS const float*)(vl + o); }
;                 float sa = (S[0] * kk[0] + S[1] * kk[1]) + (S[2] * kk[2] + S[3] * kk[3]);
;                 const f32x4 kvt = k * v;
;                 sa = -row16_sum(sa);
;                 S = S * w + (b * sa + kvt);
;                 yp[st & 15] = (S[0] * r[0] + S[1] * r[1]) + (S[2] * r[2] + S[3] * r[3]);
;                 if ((st & 15) == 15) yo[(size_t)(st - 15) * 64] = tr16_sum(yp, kq);
;                 w = wn; b = bn; k = kn; kk = kkn; r = rn; v = vn;
;             }
	v_pk_mul_f32 v[10:11], v[2:3], v[132:133]
	v_pk_fma_f32 v[10:11], v[4:5], v[134:135], v[10:11]
	v_pk_mul_f32 v[14:15], v[2:3], v[38:39]
	v_add_f32_e32 v12, v10, v11
	v_pk_fma_f32 v[14:15], v[4:5], v[40:41], v[14:15]
	v_add_f32_e64 v103, v14, v15
	v_add_f32_dpp v12, v12, v12 quad_perm:[1,0,3,2] row_mask:0xf bank_mask:0xf bound_ctrl:1
	v_pk_mul_f32 v[6:7], v[128:129], v[92:93] op_sel_hi:[1,0]
	v_pk_mul_f32 v[8:9], v[130:131], v[92:93] op_sel_hi:[1,0]
	v_add_f32_dpp v12, v12, v12 quad_perm:[2,3,0,1] row_mask:0xf bank_mask:0xf bound_ctrl:1
	v_pk_fma_f32 v[6:7], v[2:3], v[120:121], v[6:7]
	v_pk_fma_f32 v[8:9], v[4:5], v[122:123], v[8:9]
	v_add_f32_dpp v12, v12, v12 row_half_mirror row_mask:0xf bank_mask:0xf bound_ctrl:1
	ds_read_b128 v[180:183], v84 offset:8832
	ds_read_b128 v[168:171], v84 offset:8064
	v_add_f32_dpp v12, v12, v12 row_mirror row_mask:0xf bank_mask:0xf bound_ctrl:1
	ds_read_b128 v[176:179], v84 offset:8576
	ds_read_b128 v[172:175], v84 offset:8320
	ds_read_b128 v[184:187], v84 offset:9088
	v_pk_fma_f32 v[2:3], v[124:125], v[12:13], v[6:7] op_sel_hi:[1,0,1] neg_lo:[0,1,0] neg_hi:[0,1,0]
	v_pk_fma_f32 v[4:5], v[126:127], v[12:13], v[8:9] op_sel_hi:[1,0,1] neg_lo:[0,1,0] neg_hi:[0,1,0]
	s_waitcnt lgkmcnt(5)
	v_pk_mul_f32 v[10:11], v[2:3], v[156:157]
	v_pk_fma_f32 v[10:11], v[4:5], v[158:159], v[10:11]
	v_pk_mul_f32 v[14:15], v[2:3], v[136:137]
	v_add_f32_e32 v12, v10, v11
	v_pk_fma_f32 v[14:15], v[4:5], v[138:139], v[14:15]
	v_add_f32_e64 v104, v14, v15
	v_add_f32_dpp v12, v12, v12 quad_perm:[1,0,3,2] row_mask:0xf bank_mask:0xf bound_ctrl:1
	v_pk_mul_f32 v[6:7], v[152:153], v[92:93] op_sel:[0,1] op_sel_hi:[1,1]
	v_pk_mul_f32 v[8:9], v[154:155], v[92:93] op_sel:[0,1] op_sel_hi:[1,1]
	v_add_f32_dpp v12, v12, v12 quad_perm:[2,3,0,1] row_mask:0xf bank_mask:0xf bound_ctrl:1
	v_pk_fma_f32 v[6:7], v[2:3], v[144:145], v[6:7]
	v_pk_fma_f32 v[8:9], v[4:5], v[146:147], v[8:9]
	v_add_f32_dpp v12, v12, v12 row_half_mirror row_mask:0xf bank_mask:0xf bound_ctrl:1
	ds_read_b128 v[34:37], v84 offset:10176
	ds_read_b128 v[22:25], v84 offset:9408
	v_add_f32_dpp v12, v12, v12 row_mirror row_mask:0xf bank_mask:0xf bound_ctrl:1
	ds_read_b128 v[30:33], v84 offset:9920
	ds_read_b128 v[26:29], v84 offset:9664
	ds_read_b128 v[38:41], v84 offset:10432
	v_pk_fma_f32 v[2:3], v[148:149], v[12:13], v[6:7] op_sel_hi:[1,0,1] neg_lo:[0,1,0] neg_hi:[0,1,0]
	v_pk_fma_f32 v[4:5], v[150:151], v[12:13], v[8:9] op_sel_hi:[1,0,1] neg_lo:[0,1,0] neg_hi:[0,1,0]
	s_waitcnt lgkmcnt(5)
	v_pk_mul_f32 v[10:11], v[2:3], v[180:181]
	v_pk_fma_f32 v[10:11], v[4:5], v[182:183], v[10:11]
	v_pk_mul_f32 v[14:15], v[2:3], v[160:161]
	v_add_f32_e32 v12, v10, v11
	v_pk_fma_f32 v[14:15], v[4:5], v[162:163], v[14:15]
	v_add_f32_e64 v105, v14, v15
	v_add_f32_dpp v12, v12, v12 quad_perm:[1,0,3,2] row_mask:0xf bank_mask:0xf bound_ctrl:1
	v_pk_mul_f32 v[6:7], v[176:177], v[94:95] op_sel_hi:[1,0]
	v_pk_mul_f32 v[8:9], v[178:179], v[94:95] op_sel_hi:[1,0]
	v_add_f32_dpp v12, v12, v12 quad_perm:[2,3,0,1] row_mask:0xf bank_mask:0xf bound_ctrl:1
	v_pk_fma_f32 v[6:7], v[2:3], v[168:169], v[6:7]
	v_pk_fma_f32 v[8:9], v[4:5], v[170:171], v[8:9]
	v_add_f32_dpp v12, v12, v12 row_half_mirror row_mask:0xf bank_mask:0xf bound_ctrl:1
	ds_read_b128 v[132:135], v84 offset:11520
	ds_read_b128 v[120:123], v84 offset:10752
	v_add_f32_dpp v12, v12, v12 row_mirror row_mask:0xf bank_mask:0xf bound_ctrl:1
	ds_read_b128 v[128:131], v84 offset:11264
	ds_read_b128 v[116:119], v96 offset:32
	ds_read_b128 v[124:127], v84 offset:11008
	ds_read_b128 v[136:139], v84 offset:11776
	v_pk_fma_f32 v[2:3], v[172:173], v[12:13], v[6:7] op_sel_hi:[1,0,1] neg_lo:[0,1,0] neg_hi:[0,1,0]
	v_pk_fma_f32 v[4:5], v[174:175], v[12:13], v[8:9] op_sel_hi:[1,0,1] neg_lo:[0,1,0] neg_hi:[0,1,0]
	s_waitcnt lgkmcnt(6)
	v_pk_mul_f32 v[10:11], v[2:3], v[34:35]
	v_pk_fma_f32 v[10:11], v[4:5], v[36:37], v[10:11]
	v_pk_mul_f32 v[14:15], v[2:3], v[184:185]
	v_add_f32_e32 v12, v10, v11
	v_pk_fma_f32 v[14:15], v[4:5], v[186:187], v[14:15]
	v_add_f32_e64 v106, v14, v15
	v_add_f32_dpp v12, v12, v12 quad_perm:[1,0,3,2] row_mask:0xf bank_mask:0xf bound_ctrl:1
	v_pk_mul_f32 v[6:7], v[30:31], v[94:95] op_sel:[0,1] op_sel_hi:[1,1]
	v_pk_mul_f32 v[8:9], v[32:33], v[94:95] op_sel:[0,1] op_sel_hi:[1,1]
	v_add_f32_dpp v12, v12, v12 quad_perm:[2,3,0,1] row_mask:0xf bank_mask:0xf bound_ctrl:1
	v_pk_fma_f32 v[6:7], v[2:3], v[22:23], v[6:7]
	v_pk_fma_f32 v[8:9], v[4:5], v[24:25], v[8:9]
	v_add_f32_dpp v12, v12, v12 row_half_mirror row_mask:0xf bank_mask:0xf bound_ctrl:1
	ds_read_b128 v[156:159], v84 offset:12864
	ds_read_b128 v[144:147], v84 offset:12096
	v_add_f32_dpp v12, v12, v12 row_mirror row_mask:0xf bank_mask:0xf bound_ctrl:1
	ds_read_b128 v[152:155], v84 offset:12608
	ds_read_b128 v[148:151], v84 offset:12352
	ds_read_b128 v[160:163], v84 offset:13120
	v_pk_fma_f32 v[2:3], v[26:27], v[12:13], v[6:7] op_sel_hi:[1,0,1] neg_lo:[0,1,0] neg_hi:[0,1,0]
	v_pk_fma_f32 v[4:5], v[28:29], v[12:13], v[8:9] op_sel_hi:[1,0,1] neg_lo:[0,1,0] neg_hi:[0,1,0]
	s_waitcnt lgkmcnt(5)
; #define LAS __attribute__((address_space(3)))
; template <int CTRL> __device__ __forceinline__ float dpp_f(float v) { return __int_as_float(__builtin_amdgcn_update_dpp(0, __float_as_int(v), CTRL, 0xf, 0xf, true)); }
; __device__ __forceinline__ float row16_sum(float v) { v += dpp_f<0xB1>(v); v += dpp_f<0x4E>(v); v += dpp_f<0x141>(v); v += dpp_f<0x140>(v); return v; }
; __device__ __forceinline__ float tr16_sum(const float (&p)[16], int kq) {
;     const bool b3 = (kq & 8) != 0, b2 = (kq & 4) != 0, b1 = (kq & 2) != 0, b0 = (kq & 1) != 0;
;     float q[8], r[4], u[2];
; #pragma unroll
;     for (int t = 0; t < 8; ++t) { const float keep = b3 ? p[t + 8] : p[t], send = b3 ? p[t] : p[t + 8]; q[t] = keep + dpp_f<0x140>(send); }
; #pragma unroll
;     for (int t = 0; t < 4; ++t) { const float keep = b2 ? q[t + 4] : q[t], send = b2 ? q[t] : q[t + 4]; r[t] = keep + dpp_f<0x141>(send); }
; #pragma unroll
;     for (int t = 0; t < 2; ++t) { const float keep = b1 ? r[t + 2] : r[t], send = b1 ? r[t] : r[t + 2]; u[t] = keep + dpp_f<0x4E>(send); }
;     const float keep = b0 ? u[1] : u[0], send = b0 ? u[0] : u[1];
;     return keep + dpp_f<0xB1>(send);
; __device__ __forceinline__ void rwkv_scan_unit(LAS unsigned char* lds, const float* Wd, const float* V, const bf16_t* RKKB, float* Yraw, int p, int rg, int tid) {
;     ...
;             for (int st = 0; st < SCAN_CH; ++st) {
;                 f32x4 wn = w, bn = b, kn = k, kkn = kk, rn = r; float vn = v;
;                 if (st + 1 < SCAN_CH) { const int o = (st + 1) * SCAN_STEP_B;
;                     wn = *(LAS const f32x4*)(sl + o); bn = *(LAS const f32x4*)(sl + o + 256); kn = *(LAS const f32x4*)(sl + o + 512); kkn = *(LAS const f32x4*)(sl + o + 768); rn = *(LAS const f32x4*)(sl + o + 1024);
;                     vn = *(LAS const float*)(vl + o); }
;                 float sa = (S[0] * kk[0] + S[1] * kk[1]) + (S[2] * kk[2] + S[3] * kk[3]);
;                 const f32x4 kvt = k * v;
;                 sa = -row16_sum(sa);
;                 S = S * w + (b * sa + kvt);
;                 yp[st & 15] = (S[0] * r[0] + S[1] * r[1]) + (S[2] * r[2] + S[3] * r[3]);
;                 if ((st & 15) == 15) yo[(size_t)(st - 15) * 64] = tr16_sum(yp, kq);
;                 w = wn; b = bn; k = kn; kk = kkn; r = rn; v = vn;
;             }
	v_pk_mul_f32 v[10:11], v[2:3], v[132:133]
	v_pk_fma_f32 v[10:11], v[4:5], v[134:135], v[10:11]
	v_pk_mul_f32 v[14:15], v[2:3], v[38:39]
	v_add_f32_e32 v12, v10, v11
	v_pk_fma_f32 v[14:15], v[4:5], v[40:41], v[14:15]
	v_add_f32_e64 v107, v14, v15
	v_add_f32_dpp v12, v12, v12 quad_perm:[1,0,3,2] row_mask:0xf bank_mask:0xf bound_ctrl:1
	v_pk_mul_f32 v[6:7], v[128:129], v[116:117] op_sel_hi:[1,0]
	v_pk_mul_f32 v[8:9], v[130:131], v[116:117] op_sel_hi:[1,0]
	v_add_f32_dpp v12, v12, v12 quad_perm:[2,3,0,1] row_mask:0xf bank_mask:0xf bound_ctrl:1
	v_pk_fma_f32 v[6:7], v[2:3], v[120:121], v[6:7]
	v_pk_fma_f32 v[8:9], v[4:5], v[122:123], v[8:9]
	v_add_f32_dpp v12, v12, v12 row_half_mirror row_mask:0xf bank_mask:0xf bound_ctrl:1
	ds_read_b128 v[180:183], v84 offset:14208
	ds_read_b128 v[168:171], v84 offset:13440
	v_add_f32_dpp v12, v12, v12 row_mirror row_mask:0xf bank_mask:0xf bound_ctrl:1
	ds_read_b128 v[176:179], v84 offset:13952
	ds_read_b128 v[172:175], v84 offset:13696
	ds_read_b128 v[184:187], v84 offset:14464
	v_pk_fma_f32 v[2:3], v[124:125], v[12:13], v[6:7] op_sel_hi:[1,0,1] neg_lo:[0,1,0] neg_hi:[0,1,0]
	v_pk_fma_f32 v[4:5], v[126:127], v[12:13], v[8:9] op_sel_hi:[1,0,1] neg_lo:[0,1,0] neg_hi:[0,1,0]
	s_waitcnt lgkmcnt(5)
	v_pk_mul_f32 v[10:11], v[2:3], v[156:157]
	v_pk_fma_f32 v[10:11], v[4:5], v[158:159], v[10:11]
	v_pk_mul_f32 v[14:15], v[2:3], v[136:137]
	v_add_f32_e32 v12, v10, v11
	v_pk_fma_f32 v[14:15], v[4:5], v[138:139], v[14:15]
	v_add_f32_e64 v44, v14, v15
	v_add_f32_dpp v12, v12, v12 quad_perm:[1,0,3,2] row_mask:0xf bank_mask:0xf bound_ctrl:1
	v_add_f32_dpp v100, v100, v100 row_mirror row_mask:0xf bank_mask:0x3 bound_ctrl:1
	v_add_f32_dpp v100, v44, v44 row_mirror row_mask:0xf bank_mask:0xc bound_ctrl:1
	v_add_f32_dpp v12, v12, v12 quad_perm:[2,3,0,1] row_mask:0xf bank_mask:0xf bound_ctrl:1
	v_pk_mul_f32 v[6:7], v[152:153], v[116:117] op_sel:[0,1] op_sel_hi:[1,1]
	v_pk_mul_f32 v[8:9], v[154:155], v[116:117] op_sel:[0,1] op_sel_hi:[1,1]
	v_add_f32_dpp v12, v12, v12 row_half_mirror row_mask:0xf bank_mask:0xf bound_ctrl:1
	v_pk_fma_f32 v[6:7], v[2:3], v[144:145], v[6:7]
	v_pk_fma_f32 v[8:9], v[4:5], v[146:147], v[8:9]
	v_add_f32_dpp v12, v12, v12 row_mirror row_mask:0xf bank_mask:0xf bound_ctrl:1
	ds_read_b128 v[34:37], v84 offset:15552
	ds_read_b128 v[22:25], v84 offset:14784
	ds_read_b128 v[30:33], v84 offset:15296
	ds_read_b128 v[26:29], v84 offset:15040
	ds_read_b128 v[38:41], v84 offset:15808
	v_pk_fma_f32 v[2:3], v[148:149], v[12:13], v[6:7] op_sel_hi:[1,0,1] neg_lo:[0,1,0] neg_hi:[0,1,0]
	v_pk_fma_f32 v[4:5], v[150:151], v[12:13], v[8:9] op_sel_hi:[1,0,1] neg_lo:[0,1,0] neg_hi:[0,1,0]
	s_waitcnt lgkmcnt(5)
	v_pk_mul_f32 v[10:11], v[2:3], v[180:181]
	v_pk_fma_f32 v[10:11], v[4:5], v[182:183], v[10:11]
	v_pk_mul_f32 v[14:15], v[2:3], v[160:161]
	v_add_f32_e32 v12, v10, v11
	v_pk_fma_f32 v[14:15], v[4:5], v[162:163], v[14:15]
	v_add_f32_e64 v44, v14, v15
	v_add_f32_dpp v12, v12, v12 quad_perm:[1,0,3,2] row_mask:0xf bank_mask:0xf bound_ctrl:1
	v_add_f32_dpp v101, v101, v101 row_mirror row_mask:0xf bank_mask:0x3 bound_ctrl:1
	v_add_f32_dpp v101, v44, v44 row_mirror row_mask:0xf bank_mask:0xc bound_ctrl:1
	v_add_f32_dpp v12, v12, v12 quad_perm:[2,3,0,1] row_mask:0xf bank_mask:0xf bound_ctrl:1
	v_pk_mul_f32 v[6:7], v[176:177], v[118:119] op_sel_hi:[1,0]
	v_pk_mul_f32 v[8:9], v[178:179], v[118:119] op_sel_hi:[1,0]
	v_add_f32_dpp v12, v12, v12 row_half_mirror row_mask:0xf bank_mask:0xf bound_ctrl:1
	v_pk_fma_f32 v[6:7], v[2:3], v[168:169], v[6:7]
	v_pk_fma_f32 v[8:9], v[4:5], v[170:171], v[8:9]
	v_add_f32_dpp v12, v12, v12 row_mirror row_mask:0xf bank_mask:0xf bound_ctrl:1
	ds_read_b128 v[132:135], v84 offset:16896
	ds_read_b128 v[120:123], v84 offset:16128
	ds_read_b128 v[128:131], v84 offset:16640
	ds_read_b128 v[92:95], v96 offset:48
	ds_read_b128 v[124:127], v84 offset:16384
	ds_read_b128 v[136:139], v84 offset:17152
	v_pk_fma_f32 v[2:3], v[172:173], v[12:13], v[6:7] op_sel_hi:[1,0,1] neg_lo:[0,1,0] neg_hi:[0,1,0]
	v_pk_fma_f32 v[4:5], v[174:175], v[12:13], v[8:9] op_sel_hi:[1,0,1] neg_lo:[0,1,0] neg_hi:[0,1,0]
	s_waitcnt lgkmcnt(6)
	v_pk_mul_f32 v[10:11], v[2:3], v[34:35]
	v_pk_fma_f32 v[10:11], v[4:5], v[36:37], v[10:11]
	v_pk_mul_f32 v[14:15], v[2:3], v[184:185]
	v_add_f32_e32 v12, v10, v11
	v_pk_fma_f32 v[14:15], v[4:5], v[186:187], v[14:15]
	v_add_f32_e64 v44, v14, v15
	v_add_f32_dpp v12, v12, v12 quad_perm:[1,0,3,2] row_mask:0xf bank_mask:0xf bound_ctrl:1
	v_add_f32_dpp v102, v102, v102 row_mirror row_mask:0xf bank_mask:0x3 bound_ctrl:1
	v_add_f32_dpp v102, v44, v44 row_mirror row_mask:0xf bank_mask:0xc bound_ctrl:1
	v_add_f32_dpp v12, v12, v12 quad_perm:[2,3,0,1] row_mask:0xf bank_mask:0xf bound_ctrl:1
	v_pk_mul_f32 v[6:7], v[30:31], v[118:119] op_sel:[0,1] op_sel_hi:[1,1]
	v_pk_mul_f32 v[8:9], v[32:33], v[118:119] op_sel:[0,1] op_sel_hi:[1,1]
	v_add_f32_dpp v12, v12, v12 row_half_mirror row_mask:0xf bank_mask:0xf bound_ctrl:1
	v_pk_fma_f32 v[6:7], v[2:3], v[22:23], v[6:7]
	v_pk_fma_f32 v[8:9], v[4:5], v[24:25], v[8:9]
	v_add_f32_dpp v12, v12, v12 row_mirror row_mask:0xf bank_mask:0xf bound_ctrl:1
	ds_read_b128 v[156:159], v84 offset:18240
	ds_read_b128 v[144:147], v84 offset:17472
	ds_read_b128 v[152:155], v84 offset:17984
	ds_read_b128 v[148:151], v84 offset:17728
	ds_read_b128 v[160:163], v84 offset:18496
	v_pk_fma_f32 v[2:3], v[26:27], v[12:13], v[6:7] op_sel_hi:[1,0,1] neg_lo:[0,1,0] neg_hi:[0,1,0]
	v_pk_fma_f32 v[4:5], v[28:29], v[12:13], v[8:9] op_sel_hi:[1,0,1] neg_lo:[0,1,0] neg_hi:[0,1,0]
	s_waitcnt lgkmcnt(5)
; #define LAS __attribute__((address_space(3)))
; template <int CTRL> __device__ __forceinline__ float dpp_f(float v) { return __int_as_float(__builtin_amdgcn_update_dpp(0, __float_as_int(v), CTRL, 0xf, 0xf, true)); }
; __device__ __forceinline__ float row16_sum(float v) { v += dpp_f<0xB1>(v); v += dpp_f<0x4E>(v); v += dpp_f<0x141>(v); v += dpp_f<0x140>(v); return v; }
; __device__ __forceinline__ float tr16_sum(const float (&p)[16], int kq) {
;     const bool b3 = (kq & 8) != 0, b2 = (kq & 4) != 0, b1 = (kq & 2) != 0, b0 = (kq & 1) != 0;
;     float q[8], r[4], u[2];
; #pragma unroll
;     for (int t = 0; t < 8; ++t) { const float keep = b3 ? p[t + 8] : p[t], send = b3 ? p[t] : p[t + 8]; q[t] = keep + dpp_f<0x140>(send); }
; #pragma unroll
;     for (int t = 0; t < 4; ++t) { const float keep = b2 ? q[t + 4] : q[t], send = b2 ? q[t] : q[t + 4]; r[t] = keep + dpp_f<0x141>(send); }
; #pragma unroll
;     for (int t = 0; t < 2; ++t) { const float keep = b1 ? r[t + 2] : r[t], send = b1 ? r[t] : r[t + 2]; u[t] = keep + dpp_f<0x4E>(send); }
;     const float keep = b0 ? u[1] : u[0], send = b0 ? u[0] : u[1];
;     return keep + dpp_f<0xB1>(send);
; __device__ __forceinline__ void rwkv_scan_unit(LAS unsigned char* lds, const float* Wd, const float* V, const bf16_t* RKKB, float* Yraw, int p, int rg, int tid) {
;     ...
;             for (int st = 0; st < SCAN_CH; ++st) {
;                 f32x4 wn = w, bn = b, kn = k, kkn = kk, rn = r; float vn = v;
;                 if (st + 1 < SCAN_CH) { const int o = (st + 1) * SCAN_STEP_B;
;                     wn = *(LAS const f32x4*)(sl + o); bn = *(LAS const f32x4*)(sl + o + 256); kn = *(LAS const f32x4*)(sl + o + 512); kkn = *(LAS const f32x4*)(sl + o + 768); rn = *(LAS const f32x4*)(sl + o + 1024);
;                     vn = *(LAS const float*)(vl + o); }
;                 float sa = (S[0] * kk[0] + S[1] * kk[1]) + (S[2] * kk[2] + S[3] * kk[3]);
;                 const f32x4 kvt = k * v;
;                 sa = -row16_sum(sa);
;                 S = S * w + (b * sa + kvt);
;                 yp[st & 15] = (S[0] * r[0] + S[1] * r[1]) + (S[2] * r[2] + S[3] * r[3]);
;                 if ((st & 15) == 15) yo[(size_t)(st - 15) * 64] = tr16_sum(yp, kq);
;                 w = wn; b = bn; k = kn; kk = kkn; r = rn; v = vn;
;             }
	v_pk_mul_f32 v[10:11], v[2:3], v[132:133]
	v_pk_fma_f32 v[10:11], v[4:5], v[134:135], v[10:11]
	v_pk_mul_f32 v[14:15], v[2:3], v[38:39]
	v_add_f32_e32 v12, v10, v11
	v_pk_fma_f32 v[14:15], v[4:5], v[40:41], v[14:15]
	v_add_f32_e64 v44, v14, v15
	v_add_f32_dpp v12, v12, v12 quad_perm:[1,0,3,2] row_mask:0xf bank_mask:0xf bound_ctrl:1
	v_add_f32_dpp v103, v103, v103 row_mirror row_mask:0xf bank_mask:0x3 bound_ctrl:1
	v_add_f32_dpp v103, v44, v44 row_mirror row_mask:0xf bank_mask:0xc bound_ctrl:1
	v_add_f32_dpp v12, v12, v12 quad_perm:[2,3,0,1] row_mask:0xf bank_mask:0xf bound_ctrl:1
	v_pk_mul_f32 v[6:7], v[128:129], v[92:93] op_sel_hi:[1,0]
	v_pk_mul_f32 v[8:9], v[130:131], v[92:93] op_sel_hi:[1,0]
	v_add_f32_dpp v12, v12, v12 row_half_mirror row_mask:0xf bank_mask:0xf bound_ctrl:1
	v_pk_fma_f32 v[6:7], v[2:3], v[120:121], v[6:7]
	v_pk_fma_f32 v[8:9], v[4:5], v[122:123], v[8:9]
	v_add_f32_dpp v12, v12, v12 row_mirror row_mask:0xf bank_mask:0xf bound_ctrl:1
	ds_read_b128 v[180:183], v84 offset:19584
	ds_read_b128 v[168:171], v84 offset:18816
	ds_read_b128 v[176:179], v84 offset:19328
	ds_read_b128 v[172:175], v84 offset:19072
	ds_read_b128 v[184:187], v84 offset:19840
	v_pk_fma_f32 v[2:3], v[124:125], v[12:13], v[6:7] op_sel_hi:[1,0,1] neg_lo:[0,1,0] neg_hi:[0,1,0]
	v_pk_fma_f32 v[4:5], v[126:127], v[12:13], v[8:9] op_sel_hi:[1,0,1] neg_lo:[0,1,0] neg_hi:[0,1,0]
	s_waitcnt lgkmcnt(5)
	v_pk_mul_f32 v[10:11], v[2:3], v[156:157]
	v_pk_fma_f32 v[10:11], v[4:5], v[158:159], v[10:11]
	v_pk_mul_f32 v[14:15], v[2:3], v[136:137]
	v_add_f32_e32 v12, v10, v11
	v_pk_fma_f32 v[14:15], v[4:5], v[138:139], v[14:15]
	v_add_f32_e64 v44, v14, v15
	v_add_f32_dpp v12, v12, v12 quad_perm:[1,0,3,2] row_mask:0xf bank_mask:0xf bound_ctrl:1
	v_add_f32_dpp v104, v104, v104 row_mirror row_mask:0xf bank_mask:0x3 bound_ctrl:1
	v_add_f32_dpp v104, v44, v44 row_mirror row_mask:0xf bank_mask:0xc bound_ctrl:1
	v_add_f32_dpp v12, v12, v12 quad_perm:[2,3,0,1] row_mask:0xf bank_mask:0xf bound_ctrl:1
	v_pk_mul_f32 v[6:7], v[152:153], v[92:93] op_sel:[0,1] op_sel_hi:[1,1]
	v_pk_mul_f32 v[8:9], v[154:155], v[92:93] op_sel:[0,1] op_sel_hi:[1,1]
	v_add_f32_dpp v12, v12, v12 row_half_mirror row_mask:0xf bank_mask:0xf bound_ctrl:1
	v_pk_fma_f32 v[6:7], v[2:3], v[144:145], v[6:7]
	v_pk_fma_f32 v[8:9], v[4:5], v[146:147], v[8:9]
	v_add_f32_dpp v12, v12, v12 row_mirror row_mask:0xf bank_mask:0xf bound_ctrl:1
	ds_read_b128 v[34:37], v84 offset:20928
	ds_read_b128 v[22:25], v84 offset:20160
	ds_read_b128 v[30:33], v84 offset:20672
	ds_read_b128 v[26:29], v84 offset:20416
	ds_read_b128 v[38:41], v84 offset:21184
	v_pk_fma_f32 v[2:3], v[148:149], v[12:13], v[6:7] op_sel_hi:[1,0,1] neg_lo:[0,1,0] neg_hi:[0,1,0]
	v_pk_fma_f32 v[4:5], v[150:151], v[12:13], v[8:9] op_sel_hi:[1,0,1] neg_lo:[0,1,0] neg_hi:[0,1,0]
	s_waitcnt lgkmcnt(5)
	v_pk_mul_f32 v[10:11], v[2:3], v[180:181]
	v_pk_fma_f32 v[10:11], v[4:5], v[182:183], v[10:11]
	v_pk_mul_f32 v[14:15], v[2:3], v[160:161]
	v_add_f32_e32 v12, v10, v11
	v_pk_fma_f32 v[14:15], v[4:5], v[162:163], v[14:15]
	v_add_f32_e64 v44, v14, v15
	v_add_f32_dpp v12, v12, v12 quad_perm:[1,0,3,2] row_mask:0xf bank_mask:0xf bound_ctrl:1
	v_add_f32_dpp v105, v105, v105 row_mirror row_mask:0xf bank_mask:0x3 bound_ctrl:1
	v_add_f32_dpp v105, v44, v44 row_mirror row_mask:0xf bank_mask:0xc bound_ctrl:1
	v_add_f32_dpp v12, v12, v12 quad_perm:[2,3,0,1] row_mask:0xf bank_mask:0xf bound_ctrl:1
	v_pk_mul_f32 v[6:7], v[176:177], v[94:95] op_sel_hi:[1,0]
	v_pk_mul_f32 v[8:9], v[178:179], v[94:95] op_sel_hi:[1,0]
	v_add_f32_dpp v12, v12, v12 row_half_mirror row_mask:0xf bank_mask:0xf bound_ctrl:1
	v_pk_fma_f32 v[6:7], v[2:3], v[168:169], v[6:7]
	v_pk_fma_f32 v[8:9], v[4:5], v[170:171], v[8:9]
	v_add_f32_dpp v12, v12, v12 row_mirror row_mask:0xf bank_mask:0xf bound_ctrl:1
	ds_read_b128 v[132:135], v84 offset:22272
	ds_read_b128 v[120:123], v84 offset:21504
	ds_read_b128 v[128:131], v84 offset:22016
	ds_read_b128 v[116:119], v96 offset:64
	ds_read_b128 v[124:127], v84 offset:21760
	ds_read_b128 v[136:139], v84 offset:22528
	v_pk_fma_f32 v[2:3], v[172:173], v[12:13], v[6:7] op_sel_hi:[1,0,1] neg_lo:[0,1,0] neg_hi:[0,1,0]
	v_pk_fma_f32 v[4:5], v[174:175], v[12:13], v[8:9] op_sel_hi:[1,0,1] neg_lo:[0,1,0] neg_hi:[0,1,0]
	s_waitcnt lgkmcnt(6)
	v_pk_mul_f32 v[10:11], v[2:3], v[34:35]
	v_pk_fma_f32 v[10:11], v[4:5], v[36:37], v[10:11]
	v_pk_mul_f32 v[14:15], v[2:3], v[184:185]
	v_add_f32_e32 v12, v10, v11
	v_pk_fma_f32 v[14:15], v[4:5], v[186:187], v[14:15]
	v_add_f32_e64 v44, v14, v15
	v_add_f32_dpp v12, v12, v12 quad_perm:[1,0,3,2] row_mask:0xf bank_mask:0xf bound_ctrl:1
	v_add_f32_dpp v106, v106, v106 row_mirror row_mask:0xf bank_mask:0x3 bound_ctrl:1
	v_add_f32_dpp v106, v44, v44 row_mirror row_mask:0xf bank_mask:0xc bound_ctrl:1
	v_add_f32_dpp v12, v12, v12 quad_perm:[2,3,0,1] row_mask:0xf bank_mask:0xf bound_ctrl:1
	v_pk_mul_f32 v[6:7], v[30:31], v[94:95] op_sel:[0,1] op_sel_hi:[1,1]
	v_pk_mul_f32 v[8:9], v[32:33], v[94:95] op_sel:[0,1] op_sel_hi:[1,1]
	v_add_f32_dpp v12, v12, v12 row_half_mirror row_mask:0xf bank_mask:0xf bound_ctrl:1
	v_pk_fma_f32 v[6:7], v[2:3], v[22:23], v[6:7]
	v_pk_fma_f32 v[8:9], v[4:5], v[24:25], v[8:9]
	v_add_f32_dpp v12, v12, v12 row_mirror row_mask:0xf bank_mask:0xf bound_ctrl:1
	ds_read_b128 v[156:159], v84 offset:23616
	ds_read_b128 v[144:147], v84 offset:22848
	ds_read_b128 v[152:155], v84 offset:23360
	ds_read_b128 v[148:151], v84 offset:23104
	ds_read_b128 v[160:163], v84 offset:23872
	v_pk_fma_f32 v[2:3], v[26:27], v[12:13], v[6:7] op_sel_hi:[1,0,1] neg_lo:[0,1,0] neg_hi:[0,1,0]
	v_pk_fma_f32 v[4:5], v[28:29], v[12:13], v[8:9] op_sel_hi:[1,0,1] neg_lo:[0,1,0] neg_hi:[0,1,0]
	s_waitcnt lgkmcnt(5)
; #define LAS __attribute__((address_space(3)))
; template <int CTRL> __device__ __forceinline__ float dpp_f(float v) { return __int_as_float(__builtin_amdgcn_update_dpp(0, __float_as_int(v), CTRL, 0xf, 0xf, true)); }
; __device__ __forceinline__ float row16_sum(float v) { v += dpp_f<0xB1>(v); v += dpp_f<0x4E>(v); v += dpp_f<0x141>(v); v += dpp_f<0x140>(v); return v; }
; __device__ __forceinline__ float tr16_sum(const float (&p)[16], int kq) {
;     const bool b3 = (kq & 8) != 0, b2 = (kq & 4) != 0, b1 = (kq & 2) != 0, b0 = (kq & 1) != 0;
;     float q[8], r[4], u[2];
; #pragma unroll
;     for (int t = 0; t < 8; ++t) { const float keep = b3 ? p[t + 8] : p[t], send = b3 ? p[t] : p[t + 8]; q[t] = keep + dpp_f<0x140>(send); }
; #pragma unroll
;     for (int t = 0; t < 4; ++t) { const float keep = b2 ? q[t + 4] : q[t], send = b2 ? q[t] : q[t + 4]; r[t] = keep + dpp_f<0x141>(send); }
; #pragma unroll
;     for (int t = 0; t < 2; ++t) { const float keep = b1 ? r[t + 2] : r[t], send = b1 ? r[t] : r[t + 2]; u[t] = keep + dpp_f<0x4E>(send); }
;     const float keep = b0 ? u[1] : u[0], send = b0 ? u[0] : u[1];
;     return keep + dpp_f<0xB1>(send);
; __device__ __forceinline__ void rwkv_scan_unit(LAS unsigned char* lds, const float* Wd, const float* V, const bf16_t* RKKB, float* Yraw, int p, int rg, int tid) {
;     ...
;             for (int st = 0; st < SCAN_CH; ++st) {
;                 f32x4 wn = w, bn = b, kn = k, kkn = kk, rn = r; float vn = v;
;                 if (st + 1 < SCAN_CH) { const int o = (st + 1) * SCAN_STEP_B;
;                     wn = *(LAS const f32x4*)(sl + o); bn = *(LAS const f32x4*)(sl + o + 256); kn = *(LAS const f32x4*)(sl + o + 512); kkn = *(LAS const f32x4*)(sl + o + 768); rn = *(LAS const f32x4*)(sl + o + 1024);
;                     vn = *(LAS const float*)(vl + o); }
;                 float sa = (S[0] * kk[0] + S[1] * kk[1]) + (S[2] * kk[2] + S[3] * kk[3]);
;                 const f32x4 kvt = k * v;
;                 sa = -row16_sum(sa);
;                 S = S * w + (b * sa + kvt);
;                 yp[st & 15] = (S[0] * r[0] + S[1] * r[1]) + (S[2] * r[2] + S[3] * r[3]);
;                 if ((st & 15) == 15) yo[(size_t)(st - 15) * 64] = tr16_sum(yp, kq);
;                 w = wn; b = bn; k = kn; kk = kkn; r = rn; v = vn;
;             }
	v_pk_mul_f32 v[10:11], v[2:3], v[132:133]
	v_pk_fma_f32 v[10:11], v[4:5], v[134:135], v[10:11]
	v_pk_mul_f32 v[14:15], v[2:3], v[38:39]
	v_add_f32_e32 v12, v10, v11
	v_pk_fma_f32 v[14:15], v[4:5], v[40:41], v[14:15]
	v_add_f32_e64 v44, v14, v15
	v_add_f32_dpp v107, v107, v107 row_mirror row_mask:0xf bank_mask:0x3 bound_ctrl:1
	s_nop 0
	v_add_f32_dpp v107, v44, v44 row_mirror row_mask:0xf bank_mask:0xc bound_ctrl:1
	v_add_f32_dpp v12, v12, v12 quad_perm:[1,0,3,2] row_mask:0xf bank_mask:0xf bound_ctrl:1
	v_pk_mul_f32 v[6:7], v[128:129], v[116:117] op_sel_hi:[1,0]
	v_pk_mul_f32 v[8:9], v[130:131], v[116:117] op_sel_hi:[1,0]
	v_pk_fma_f32 v[6:7], v[2:3], v[120:121], v[6:7]
	v_pk_fma_f32 v[8:9], v[4:5], v[122:123], v[8:9]
	v_add_f32_dpp v12, v12, v12 quad_perm:[2,3,0,1] row_mask:0xf bank_mask:0xf bound_ctrl:1
	ds_read_b128 v[180:183], v84 offset:24960
	ds_read_b128 v[168:171], v84 offset:24192
	ds_read_b128 v[176:179], v84 offset:24704
	ds_read_b128 v[172:175], v84 offset:24448
	v_add_f32_dpp v12, v12, v12 row_half_mirror row_mask:0xf bank_mask:0xf bound_ctrl:1
	ds_read_b128 v[184:187], v84 offset:25216
	v_add_f32_dpp v100, v100, v100 row_half_mirror row_mask:0xf bank_mask:0x5 bound_ctrl:1
	v_add_f32_dpp v100, v104, v104 row_half_mirror row_mask:0xf bank_mask:0xa bound_ctrl:1
	v_add_f32_dpp v101, v101, v101 row_half_mirror row_mask:0xf bank_mask:0x5 bound_ctrl:1
	v_add_f32_dpp v12, v12, v12 row_mirror row_mask:0xf bank_mask:0xf bound_ctrl:1
	v_add_f32_dpp v101, v105, v105 row_half_mirror row_mask:0xf bank_mask:0xa bound_ctrl:1
	v_add_f32_dpp v102, v102, v102 row_half_mirror row_mask:0xf bank_mask:0x5 bound_ctrl:1
	v_add_f32_dpp v102, v106, v106 row_half_mirror row_mask:0xf bank_mask:0xa bound_ctrl:1
	v_add_f32_dpp v103, v103, v103 row_half_mirror row_mask:0xf bank_mask:0x5 bound_ctrl:1
	v_add_f32_dpp v103, v107, v107 row_half_mirror row_mask:0xf bank_mask:0xa bound_ctrl:1
	v_cndmask_b32_e64 v16, v102, v100, s[8:9]
	v_pk_fma_f32 v[2:3], v[124:125], v[12:13], v[6:7] op_sel_hi:[1,0,1] neg_lo:[0,1,0] neg_hi:[0,1,0]
	v_pk_fma_f32 v[4:5], v[126:127], v[12:13], v[8:9] op_sel_hi:[1,0,1] neg_lo:[0,1,0] neg_hi:[0,1,0]
	s_waitcnt lgkmcnt(5)
	v_pk_mul_f32 v[10:11], v[2:3], v[156:157]
	v_pk_fma_f32 v[10:11], v[4:5], v[158:159], v[10:11]
	v_pk_mul_f32 v[14:15], v[2:3], v[136:137]
	v_add_f32_e32 v12, v10, v11
	v_pk_fma_f32 v[14:15], v[4:5], v[138:139], v[14:15]
	v_add_f32_e64 v108, v14, v15
	v_pk_mul_f32 v[6:7], v[152:153], v[116:117] op_sel:[0,1] op_sel_hi:[1,1]
	v_pk_mul_f32 v[8:9], v[154:155], v[116:117] op_sel:[0,1] op_sel_hi:[1,1]
	v_add_f32_dpp v12, v12, v12 quad_perm:[1,0,3,2] row_mask:0xf bank_mask:0xf bound_ctrl:1
	v_pk_fma_f32 v[6:7], v[2:3], v[144:145], v[6:7]
	v_pk_fma_f32 v[8:9], v[4:5], v[146:147], v[8:9]
	ds_read_b128 v[34:37], v84 offset:26304
	ds_read_b128 v[22:25], v84 offset:25536
	v_add_f32_dpp v12, v12, v12 quad_perm:[2,3,0,1] row_mask:0xf bank_mask:0xf bound_ctrl:1
	ds_read_b128 v[30:33], v84 offset:26048
	ds_read_b128 v[26:29], v84 offset:25792
	ds_read_b128 v[38:41], v84 offset:26560
	v_cndmask_b32_e64 v17, v100, v102, s[8:9]
	v_add_f32_dpp v12, v12, v12 row_half_mirror row_mask:0xf bank_mask:0xf bound_ctrl:1
	s_nop 0
	v_add_f32_dpp v16, v17, v16 quad_perm:[2,3,0,1] row_mask:0xf bank_mask:0xf bound_ctrl:1
	v_cndmask_b32_e64 v18, v103, v101, s[8:9]
	v_cndmask_b32_e64 v19, v101, v103, s[8:9]
	s_nop 1
	v_add_f32_dpp v18, v19, v18 quad_perm:[2,3,0,1] row_mask:0xf bank_mask:0xf bound_ctrl:1
	v_add_f32_dpp v12, v12, v12 row_mirror row_mask:0xf bank_mask:0xf bound_ctrl:1
	v_cndmask_b32_e64 v17, v18, v16, s[10:11]
	v_cndmask_b32_e64 v19, v16, v18, s[10:11]
	s_nop 1
	v_add_f32_dpp v17, v19, v17 quad_perm:[1,0,3,2] row_mask:0xf bank_mask:0xf bound_ctrl:1
	global_store_dword v[88:89], v17, off
	v_pk_fma_f32 v[2:3], v[148:149], v[12:13], v[6:7] op_sel_hi:[1,0,1] neg_lo:[0,1,0] neg_hi:[0,1,0]
	v_pk_fma_f32 v[4:5], v[150:151], v[12:13], v[8:9] op_sel_hi:[1,0,1] neg_lo:[0,1,0] neg_hi:[0,1,0]
	s_waitcnt lgkmcnt(5)
	v_pk_mul_f32 v[10:11], v[2:3], v[180:181]
	v_pk_fma_f32 v[10:11], v[4:5], v[182:183], v[10:11]
	v_pk_mul_f32 v[14:15], v[2:3], v[160:161]
	v_add_f32_e32 v12, v10, v11
	v_pk_fma_f32 v[14:15], v[4:5], v[162:163], v[14:15]
	v_add_f32_e64 v109, v14, v15
	v_add_f32_dpp v12, v12, v12 quad_perm:[1,0,3,2] row_mask:0xf bank_mask:0xf bound_ctrl:1
	v_pk_mul_f32 v[6:7], v[176:177], v[118:119] op_sel_hi:[1,0]
	v_pk_mul_f32 v[8:9], v[178:179], v[118:119] op_sel_hi:[1,0]
	v_add_f32_dpp v12, v12, v12 quad_perm:[2,3,0,1] row_mask:0xf bank_mask:0xf bound_ctrl:1
	v_pk_fma_f32 v[6:7], v[2:3], v[168:169], v[6:7]
	v_pk_fma_f32 v[8:9], v[4:5], v[170:171], v[8:9]
	v_add_f32_dpp v12, v12, v12 row_half_mirror row_mask:0xf bank_mask:0xf bound_ctrl:1
	ds_read_b128 v[132:135], v84 offset:27648
	ds_read_b128 v[120:123], v84 offset:26880
	v_add_f32_dpp v12, v12, v12 row_mirror row_mask:0xf bank_mask:0xf bound_ctrl:1
	ds_read_b128 v[128:131], v84 offset:27392
	ds_read_b128 v[92:95], v96 offset:80
	ds_read_b128 v[124:127], v84 offset:27136
	ds_read_b128 v[136:139], v84 offset:27904
	v_pk_fma_f32 v[2:3], v[172:173], v[12:13], v[6:7] op_sel_hi:[1,0,1] neg_lo:[0,1,0] neg_hi:[0,1,0]
	v_pk_fma_f32 v[4:5], v[174:175], v[12:13], v[8:9] op_sel_hi:[1,0,1] neg_lo:[0,1,0] neg_hi:[0,1,0]
	s_waitcnt lgkmcnt(6)
; #define LAS __attribute__((address_space(3)))
; __device__ __forceinline__ float row16_sum(float v) { v += dpp_f<0xB1>(v); v += dpp_f<0x4E>(v); v += dpp_f<0x141>(v); v += dpp_f<0x140>(v); return v; }
; __device__ __forceinline__ void rwkv_scan_unit(LAS unsigned char* lds, const float* Wd, const float* V, const bf16_t* RKKB, float* Yraw, int p, int rg, int tid) {
;     ...
;             for (int st = 0; st < SCAN_CH; ++st) {
;                 f32x4 wn = w, bn = b, kn = k, kkn = kk, rn = r; float vn = v;
;                 if (st + 1 < SCAN_CH) { const int o = (st + 1) * SCAN_STEP_B;
;                     wn = *(LAS const f32x4*)(sl + o); bn = *(LAS const f32x4*)(sl + o + 256); kn = *(LAS const f32x4*)(sl + o + 512); kkn = *(LAS const f32x4*)(sl + o + 768); rn = *(LAS const f32x4*)(sl + o + 1024);
;                     vn = *(LAS const float*)(vl + o); }
;                 float sa = (S[0] * kk[0] + S[1] * kk[1]) + (S[2] * kk[2] + S[3] * kk[3]);
;                 const f32x4 kvt = k * v;
;                 sa = -row16_sum(sa);
;                 S = S * w + (b * sa + kvt);
;                 yp[st & 15] = (S[0] * r[0] + S[1] * r[1]) + (S[2] * r[2] + S[3] * r[3]);
;                 if ((st & 15) == 15) yo[(size_t)(st - 15) * 64] = tr16_sum(yp, kq);
;                 w = wn; b = bn; k = kn; kk = kkn; r = rn; v = vn;
;             }
	v_pk_mul_f32 v[10:11], v[2:3], v[34:35]
	v_pk_fma_f32 v[10:11], v[4:5], v[36:37], v[10:11]
	v_pk_mul_f32 v[14:15], v[2:3], v[184:185]
	v_add_f32_e32 v12, v10, v11
	v_pk_fma_f32 v[14:15], v[4:5], v[186:187], v[14:15]
	v_add_f32_e64 v110, v14, v15
	v_add_f32_dpp v12, v12, v12 quad_perm:[1,0,3,2] row_mask:0xf bank_mask:0xf bound_ctrl:1
	v_pk_mul_f32 v[6:7], v[30:31], v[118:119] op_sel:[0,1] op_sel_hi:[1,1]
	v_pk_mul_f32 v[8:9], v[32:33], v[118:119] op_sel:[0,1] op_sel_hi:[1,1]
	v_add_f32_dpp v12, v12, v12 quad_perm:[2,3,0,1] row_mask:0xf bank_mask:0xf bound_ctrl:1
	v_pk_fma_f32 v[6:7], v[2:3], v[22:23], v[6:7]
	v_pk_fma_f32 v[8:9], v[4:5], v[24:25], v[8:9]
	v_add_f32_dpp v12, v12, v12 row_half_mirror row_mask:0xf bank_mask:0xf bound_ctrl:1
	ds_read_b128 v[156:159], v84 offset:28992
	ds_read_b128 v[144:147], v84 offset:28224
	v_add_f32_dpp v12, v12, v12 row_mirror row_mask:0xf bank_mask:0xf bound_ctrl:1
	ds_read_b128 v[152:155], v84 offset:28736
	ds_read_b128 v[148:151], v84 offset:28480
	ds_read_b128 v[160:163], v84 offset:29248
	v_pk_fma_f32 v[2:3], v[26:27], v[12:13], v[6:7] op_sel_hi:[1,0,1] neg_lo:[0,1,0] neg_hi:[0,1,0]
	v_pk_fma_f32 v[4:5], v[28:29], v[12:13], v[8:9] op_sel_hi:[1,0,1] neg_lo:[0,1,0] neg_hi:[0,1,0]
	s_waitcnt lgkmcnt(5)
	v_pk_mul_f32 v[10:11], v[2:3], v[132:133]
	v_pk_fma_f32 v[10:11], v[4:5], v[134:135], v[10:11]
	v_pk_mul_f32 v[14:15], v[2:3], v[38:39]
	v_add_f32_e32 v12, v10, v11
	v_pk_fma_f32 v[14:15], v[4:5], v[40:41], v[14:15]
	v_add_f32_e64 v111, v14, v15
	v_add_f32_dpp v12, v12, v12 quad_perm:[1,0,3,2] row_mask:0xf bank_mask:0xf bound_ctrl:1
	v_pk_mul_f32 v[6:7], v[128:129], v[92:93] op_sel_hi:[1,0]
	v_pk_mul_f32 v[8:9], v[130:131], v[92:93] op_sel_hi:[1,0]
	v_add_f32_dpp v12, v12, v12 quad_perm:[2,3,0,1] row_mask:0xf bank_mask:0xf bound_ctrl:1
	v_pk_fma_f32 v[6:7], v[2:3], v[120:121], v[6:7]
	v_pk_fma_f32 v[8:9], v[4:5], v[122:123], v[8:9]
	v_add_f32_dpp v12, v12, v12 row_half_mirror row_mask:0xf bank_mask:0xf bound_ctrl:1
	ds_read_b128 v[180:183], v84 offset:30336
	ds_read_b128 v[168:171], v84 offset:29568
	v_add_f32_dpp v12, v12, v12 row_mirror row_mask:0xf bank_mask:0xf bound_ctrl:1
	ds_read_b128 v[176:179], v84 offset:30080
	ds_read_b128 v[172:175], v84 offset:29824
	ds_read_b128 v[184:187], v84 offset:30592
	v_pk_fma_f32 v[2:3], v[124:125], v[12:13], v[6:7] op_sel_hi:[1,0,1] neg_lo:[0,1,0] neg_hi:[0,1,0]
	v_pk_fma_f32 v[4:5], v[126:127], v[12:13], v[8:9] op_sel_hi:[1,0,1] neg_lo:[0,1,0] neg_hi:[0,1,0]
	s_waitcnt lgkmcnt(5)
	v_pk_mul_f32 v[10:11], v[2:3], v[156:157]
	v_pk_fma_f32 v[10:11], v[4:5], v[158:159], v[10:11]
	v_pk_mul_f32 v[14:15], v[2:3], v[136:137]
	v_add_f32_e32 v12, v10, v11
	v_pk_fma_f32 v[14:15], v[4:5], v[138:139], v[14:15]
	v_add_f32_e64 v112, v14, v15
	v_add_f32_dpp v12, v12, v12 quad_perm:[1,0,3,2] row_mask:0xf bank_mask:0xf bound_ctrl:1
	v_pk_mul_f32 v[6:7], v[152:153], v[92:93] op_sel:[0,1] op_sel_hi:[1,1]
	v_pk_mul_f32 v[8:9], v[154:155], v[92:93] op_sel:[0,1] op_sel_hi:[1,1]
	v_add_f32_dpp v12, v12, v12 quad_perm:[2,3,0,1] row_mask:0xf bank_mask:0xf bound_ctrl:1
	v_pk_fma_f32 v[6:7], v[2:3], v[144:145], v[6:7]
	v_pk_fma_f32 v[8:9], v[4:5], v[146:147], v[8:9]
	v_add_f32_dpp v12, v12, v12 row_half_mirror row_mask:0xf bank_mask:0xf bound_ctrl:1
	ds_read_b128 v[34:37], v84 offset:31680
	ds_read_b128 v[22:25], v84 offset:30912
	v_add_f32_dpp v12, v12, v12 row_mirror row_mask:0xf bank_mask:0xf bound_ctrl:1
	ds_read_b128 v[30:33], v84 offset:31424
	ds_read_b128 v[26:29], v84 offset:31168
	ds_read_b128 v[38:41], v84 offset:31936
	v_pk_fma_f32 v[2:3], v[148:149], v[12:13], v[6:7] op_sel_hi:[1,0,1] neg_lo:[0,1,0] neg_hi:[0,1,0]
	v_pk_fma_f32 v[4:5], v[150:151], v[12:13], v[8:9] op_sel_hi:[1,0,1] neg_lo:[0,1,0] neg_hi:[0,1,0]
	s_waitcnt lgkmcnt(5)
	v_pk_mul_f32 v[10:11], v[2:3], v[180:181]
	v_pk_fma_f32 v[10:11], v[4:5], v[182:183], v[10:11]
	v_pk_mul_f32 v[14:15], v[2:3], v[160:161]
	v_add_f32_e32 v12, v10, v11
	v_pk_fma_f32 v[14:15], v[4:5], v[162:163], v[14:15]
	v_add_f32_e64 v113, v14, v15
	v_add_f32_dpp v12, v12, v12 quad_perm:[1,0,3,2] row_mask:0xf bank_mask:0xf bound_ctrl:1
	v_pk_mul_f32 v[6:7], v[176:177], v[94:95] op_sel_hi:[1,0]
	v_pk_mul_f32 v[8:9], v[178:179], v[94:95] op_sel_hi:[1,0]
	v_add_f32_dpp v12, v12, v12 quad_perm:[2,3,0,1] row_mask:0xf bank_mask:0xf bound_ctrl:1
	v_pk_fma_f32 v[6:7], v[2:3], v[168:169], v[6:7]
	v_pk_fma_f32 v[8:9], v[4:5], v[170:171], v[8:9]
	v_add_f32_dpp v12, v12, v12 row_half_mirror row_mask:0xf bank_mask:0xf bound_ctrl:1
	ds_read_b128 v[132:135], v84 offset:33024
	ds_read_b128 v[120:123], v84 offset:32256
	v_add_f32_dpp v12, v12, v12 row_mirror row_mask:0xf bank_mask:0xf bound_ctrl:1
	ds_read_b128 v[128:131], v84 offset:32768
	ds_read_b128 v[116:119], v96 offset:96
	ds_read_b128 v[124:127], v84 offset:32512
	ds_read_b128 v[136:139], v84 offset:33280
	v_pk_fma_f32 v[2:3], v[172:173], v[12:13], v[6:7] op_sel_hi:[1,0,1] neg_lo:[0,1,0] neg_hi:[0,1,0]
	v_pk_fma_f32 v[4:5], v[174:175], v[12:13], v[8:9] op_sel_hi:[1,0,1] neg_lo:[0,1,0] neg_hi:[0,1,0]
	s_waitcnt lgkmcnt(6)
; #define LAS __attribute__((address_space(3)))
; template <int CTRL> __device__ __forceinline__ float dpp_f(float v) { return __int_as_float(__builtin_amdgcn_update_dpp(0, __float_as_int(v), CTRL, 0xf, 0xf, true)); }
; __device__ __forceinline__ float row16_sum(float v) { v += dpp_f<0xB1>(v); v += dpp_f<0x4E>(v); v += dpp_f<0x141>(v); v += dpp_f<0x140>(v); return v; }
; __device__ __forceinline__ float tr16_sum(const float (&p)[16], int kq) {
;     const bool b3 = (kq & 8) != 0, b2 = (kq & 4) != 0, b1 = (kq & 2) != 0, b0 = (kq & 1) != 0;
;     float q[8], r[4], u[2];
; #pragma unroll
;     for (int t = 0; t < 8; ++t) { const float keep = b3 ? p[t + 8] : p[t], send = b3 ? p[t] : p[t + 8]; q[t] = keep + dpp_f<0x140>(send); }
; #pragma unroll
;     for (int t = 0; t < 4; ++t) { const float keep = b2 ? q[t + 4] : q[t], send = b2 ? q[t] : q[t + 4]; r[t] = keep + dpp_f<0x141>(send); }
; #pragma unroll
;     for (int t = 0; t < 2; ++t) { const float keep = b1 ? r[t + 2] : r[t], send = b1 ? r[t] : r[t + 2]; u[t] = keep + dpp_f<0x4E>(send); }
;     const float keep = b0 ? u[1] : u[0], send = b0 ? u[0] : u[1];
;     return keep + dpp_f<0xB1>(send);
; __device__ __forceinline__ void rwkv_scan_unit(LAS unsigned char* lds, const float* Wd, const float* V, const bf16_t* RKKB, float* Yraw, int p, int rg, int tid) {
;     ...
;             for (int st = 0; st < SCAN_CH; ++st) {
;                 f32x4 wn = w, bn = b, kn = k, kkn = kk, rn = r; float vn = v;
;                 if (st + 1 < SCAN_CH) { const int o = (st + 1) * SCAN_STEP_B;
;                     wn = *(LAS const f32x4*)(sl + o); bn = *(LAS const f32x4*)(sl + o + 256); kn = *(LAS const f32x4*)(sl + o + 512); kkn = *(LAS const f32x4*)(sl + o + 768); rn = *(LAS const f32x4*)(sl + o + 1024);
;                     vn = *(LAS const float*)(vl + o); }
;                 float sa = (S[0] * kk[0] + S[1] * kk[1]) + (S[2] * kk[2] + S[3] * kk[3]);
;                 const f32x4 kvt = k * v;
;                 sa = -row16_sum(sa);
;                 S = S * w + (b * sa + kvt);
;                 yp[st & 15] = (S[0] * r[0] + S[1] * r[1]) + (S[2] * r[2] + S[3] * r[3]);
;                 if ((st & 15) == 15) yo[(size_t)(st - 15) * 64] = tr16_sum(yp, kq);
;                 w = wn; b = bn; k = kn; kk = kkn; r = rn; v = vn;
;             }
	v_pk_mul_f32 v[10:11], v[2:3], v[34:35]
	v_pk_fma_f32 v[10:11], v[4:5], v[36:37], v[10:11]
	v_pk_mul_f32 v[14:15], v[2:3], v[184:185]
	v_add_f32_e32 v12, v10, v11
	v_pk_fma_f32 v[14:15], v[4:5], v[186:187], v[14:15]
	v_add_f32_e64 v114, v14, v15
	v_add_f32_dpp v12, v12, v12 quad_perm:[1,0,3,2] row_mask:0xf bank_mask:0xf bound_ctrl:1
	v_pk_mul_f32 v[6:7], v[30:31], v[94:95] op_sel:[0,1] op_sel_hi:[1,1]
	v_pk_mul_f32 v[8:9], v[32:33], v[94:95] op_sel:[0,1] op_sel_hi:[1,1]
	v_add_f32_dpp v12, v12, v12 quad_perm:[2,3,0,1] row_mask:0xf bank_mask:0xf bound_ctrl:1
	v_pk_fma_f32 v[6:7], v[2:3], v[22:23], v[6:7]
	v_pk_fma_f32 v[8:9], v[4:5], v[24:25], v[8:9]
	v_add_f32_dpp v12, v12, v12 row_half_mirror row_mask:0xf bank_mask:0xf bound_ctrl:1
	ds_read_b128 v[156:159], v84 offset:34368
	ds_read_b128 v[144:147], v84 offset:33600
	v_add_f32_dpp v12, v12, v12 row_mirror row_mask:0xf bank_mask:0xf bound_ctrl:1
	ds_read_b128 v[152:155], v84 offset:34112
	ds_read_b128 v[148:151], v84 offset:33856
	ds_read_b128 v[160:163], v84 offset:34624
	v_pk_fma_f32 v[2:3], v[26:27], v[12:13], v[6:7] op_sel_hi:[1,0,1] neg_lo:[0,1,0] neg_hi:[0,1,0]
	v_pk_fma_f32 v[4:5], v[28:29], v[12:13], v[8:9] op_sel_hi:[1,0,1] neg_lo:[0,1,0] neg_hi:[0,1,0]
	s_waitcnt lgkmcnt(5)
	v_pk_mul_f32 v[10:11], v[2:3], v[132:133]
	v_pk_fma_f32 v[10:11], v[4:5], v[134:135], v[10:11]
	v_pk_mul_f32 v[14:15], v[2:3], v[38:39]
	v_add_f32_e32 v12, v10, v11
	v_pk_fma_f32 v[14:15], v[4:5], v[40:41], v[14:15]
	v_add_f32_e64 v115, v14, v15
	v_add_f32_dpp v12, v12, v12 quad_perm:[1,0,3,2] row_mask:0xf bank_mask:0xf bound_ctrl:1
	v_pk_mul_f32 v[6:7], v[128:129], v[116:117] op_sel_hi:[1,0]
	v_pk_mul_f32 v[8:9], v[130:131], v[116:117] op_sel_hi:[1,0]
	v_add_f32_dpp v12, v12, v12 quad_perm:[2,3,0,1] row_mask:0xf bank_mask:0xf bound_ctrl:1
	v_pk_fma_f32 v[6:7], v[2:3], v[120:121], v[6:7]
	v_pk_fma_f32 v[8:9], v[4:5], v[122:123], v[8:9]
	v_add_f32_dpp v12, v12, v12 row_half_mirror row_mask:0xf bank_mask:0xf bound_ctrl:1
	ds_read_b128 v[180:183], v84 offset:35712
	ds_read_b128 v[168:171], v84 offset:34944
	v_add_f32_dpp v12, v12, v12 row_mirror row_mask:0xf bank_mask:0xf bound_ctrl:1
	ds_read_b128 v[176:179], v84 offset:35456
	ds_read_b128 v[172:175], v84 offset:35200
	ds_read_b128 v[184:187], v84 offset:35968
	v_pk_fma_f32 v[2:3], v[124:125], v[12:13], v[6:7] op_sel_hi:[1,0,1] neg_lo:[0,1,0] neg_hi:[0,1,0]
	v_pk_fma_f32 v[4:5], v[126:127], v[12:13], v[8:9] op_sel_hi:[1,0,1] neg_lo:[0,1,0] neg_hi:[0,1,0]
	s_waitcnt lgkmcnt(5)
	v_pk_mul_f32 v[10:11], v[2:3], v[156:157]
	v_pk_fma_f32 v[10:11], v[4:5], v[158:159], v[10:11]
	v_pk_mul_f32 v[14:15], v[2:3], v[136:137]
	v_add_f32_e32 v12, v10, v11
	v_pk_fma_f32 v[14:15], v[4:5], v[138:139], v[14:15]
	v_add_f32_e64 v44, v14, v15
	v_add_f32_dpp v12, v12, v12 quad_perm:[1,0,3,2] row_mask:0xf bank_mask:0xf bound_ctrl:1
	v_add_f32_dpp v108, v108, v108 row_mirror row_mask:0xf bank_mask:0x3 bound_ctrl:1
	v_add_f32_dpp v108, v44, v44 row_mirror row_mask:0xf bank_mask:0xc bound_ctrl:1
	v_add_f32_dpp v12, v12, v12 quad_perm:[2,3,0,1] row_mask:0xf bank_mask:0xf bound_ctrl:1
	v_pk_mul_f32 v[6:7], v[152:153], v[116:117] op_sel:[0,1] op_sel_hi:[1,1]
	v_pk_mul_f32 v[8:9], v[154:155], v[116:117] op_sel:[0,1] op_sel_hi:[1,1]
	v_add_f32_dpp v12, v12, v12 row_half_mirror row_mask:0xf bank_mask:0xf bound_ctrl:1
	v_pk_fma_f32 v[6:7], v[2:3], v[144:145], v[6:7]
	v_pk_fma_f32 v[8:9], v[4:5], v[146:147], v[8:9]
	v_add_f32_dpp v12, v12, v12 row_mirror row_mask:0xf bank_mask:0xf bound_ctrl:1
	ds_read_b128 v[34:37], v84 offset:37056
	ds_read_b128 v[22:25], v84 offset:36288
	ds_read_b128 v[30:33], v84 offset:36800
	ds_read_b128 v[26:29], v84 offset:36544
	ds_read_b128 v[38:41], v84 offset:37312
	v_pk_fma_f32 v[2:3], v[148:149], v[12:13], v[6:7] op_sel_hi:[1,0,1] neg_lo:[0,1,0] neg_hi:[0,1,0]
	v_pk_fma_f32 v[4:5], v[150:151], v[12:13], v[8:9] op_sel_hi:[1,0,1] neg_lo:[0,1,0] neg_hi:[0,1,0]
	s_waitcnt lgkmcnt(5)
	v_pk_mul_f32 v[10:11], v[2:3], v[180:181]
	v_pk_fma_f32 v[10:11], v[4:5], v[182:183], v[10:11]
	v_pk_mul_f32 v[14:15], v[2:3], v[160:161]
	v_add_f32_e32 v12, v10, v11
	v_pk_fma_f32 v[14:15], v[4:5], v[162:163], v[14:15]
	v_add_f32_e64 v44, v14, v15
	v_add_f32_dpp v12, v12, v12 quad_perm:[1,0,3,2] row_mask:0xf bank_mask:0xf bound_ctrl:1
	v_add_f32_dpp v109, v109, v109 row_mirror row_mask:0xf bank_mask:0x3 bound_ctrl:1
	v_add_f32_dpp v109, v44, v44 row_mirror row_mask:0xf bank_mask:0xc bound_ctrl:1
	v_add_f32_dpp v12, v12, v12 quad_perm:[2,3,0,1] row_mask:0xf bank_mask:0xf bound_ctrl:1
	v_pk_mul_f32 v[6:7], v[176:177], v[118:119] op_sel_hi:[1,0]
	v_pk_mul_f32 v[8:9], v[178:179], v[118:119] op_sel_hi:[1,0]
	v_add_f32_dpp v12, v12, v12 row_half_mirror row_mask:0xf bank_mask:0xf bound_ctrl:1
	v_pk_fma_f32 v[6:7], v[2:3], v[168:169], v[6:7]
	v_pk_fma_f32 v[8:9], v[4:5], v[170:171], v[8:9]
	v_add_f32_dpp v12, v12, v12 row_mirror row_mask:0xf bank_mask:0xf bound_ctrl:1
	ds_read_b128 v[132:135], v84 offset:38400
	ds_read_b128 v[120:123], v84 offset:37632
	ds_read_b128 v[128:131], v84 offset:38144
	ds_read_b128 v[92:95], v96 offset:112
	ds_read_b128 v[124:127], v84 offset:37888
	ds_read_b128 v[136:139], v84 offset:38656
	v_pk_fma_f32 v[2:3], v[172:173], v[12:13], v[6:7] op_sel_hi:[1,0,1] neg_lo:[0,1,0] neg_hi:[0,1,0]
	v_pk_fma_f32 v[4:5], v[174:175], v[12:13], v[8:9] op_sel_hi:[1,0,1] neg_lo:[0,1,0] neg_hi:[0,1,0]
	s_waitcnt lgkmcnt(6)
; #define LAS __attribute__((address_space(3)))
; template <int CTRL> __device__ __forceinline__ float dpp_f(float v) { return __int_as_float(__builtin_amdgcn_update_dpp(0, __float_as_int(v), CTRL, 0xf, 0xf, true)); }
; __device__ __forceinline__ float row16_sum(float v) { v += dpp_f<0xB1>(v); v += dpp_f<0x4E>(v); v += dpp_f<0x141>(v); v += dpp_f<0x140>(v); return v; }
; __device__ __forceinline__ float tr16_sum(const float (&p)[16], int kq) {
;     const bool b3 = (kq & 8) != 0, b2 = (kq & 4) != 0, b1 = (kq & 2) != 0, b0 = (kq & 1) != 0;
;     float q[8], r[4], u[2];
; #pragma unroll
;     for (int t = 0; t < 8; ++t) { const float keep = b3 ? p[t + 8] : p[t], send = b3 ? p[t] : p[t + 8]; q[t] = keep + dpp_f<0x140>(send); }
; #pragma unroll
;     for (int t = 0; t < 4; ++t) { const float keep = b2 ? q[t + 4] : q[t], send = b2 ? q[t] : q[t + 4]; r[t] = keep + dpp_f<0x141>(send); }
; #pragma unroll
;     for (int t = 0; t < 2; ++t) { const float keep = b1 ? r[t + 2] : r[t], send = b1 ? r[t] : r[t + 2]; u[t] = keep + dpp_f<0x4E>(send); }
;     const float keep = b0 ? u[1] : u[0], send = b0 ? u[0] : u[1];
;     return keep + dpp_f<0xB1>(send);
; __device__ __forceinline__ void rwkv_scan_unit(LAS unsigned char* lds, const float* Wd, const float* V, const bf16_t* RKKB, float* Yraw, int p, int rg, int tid) {
;     ...
;             for (int st = 0; st < SCAN_CH; ++st) {
;                 f32x4 wn = w, bn = b, kn = k, kkn = kk, rn = r; float vn = v;
;                 if (st + 1 < SCAN_CH) { const int o = (st + 1) * SCAN_STEP_B;
;                     wn = *(LAS const f32x4*)(sl + o); bn = *(LAS const f32x4*)(sl + o + 256); kn = *(LAS const f32x4*)(sl + o + 512); kkn = *(LAS const f32x4*)(sl + o + 768); rn = *(LAS const f32x4*)(sl + o + 1024);
;                     vn = *(LAS const float*)(vl + o); }
;                 float sa = (S[0] * kk[0] + S[1] * kk[1]) + (S[2] * kk[2] + S[3] * kk[3]);
;                 const f32x4 kvt = k * v;
;                 sa = -row16_sum(sa);
;                 S = S * w + (b * sa + kvt);
;                 yp[st & 15] = (S[0] * r[0] + S[1] * r[1]) + (S[2] * r[2] + S[3] * r[3]);
;                 if ((st & 15) == 15) yo[(size_t)(st - 15) * 64] = tr16_sum(yp, kq);
;                 w = wn; b = bn; k = kn; kk = kkn; r = rn; v = vn;
;             }
	v_pk_mul_f32 v[10:11], v[2:3], v[34:35]
	v_pk_fma_f32 v[10:11], v[4:5], v[36:37], v[10:11]
	v_pk_mul_f32 v[14:15], v[2:3], v[184:185]
	v_add_f32_e32 v12, v10, v11
	v_pk_fma_f32 v[14:15], v[4:5], v[186:187], v[14:15]
	v_add_f32_e64 v44, v14, v15
	v_add_f32_dpp v12, v12, v12 quad_perm:[1,0,3,2] row_mask:0xf bank_mask:0xf bound_ctrl:1
	v_add_f32_dpp v110, v110, v110 row_mirror row_mask:0xf bank_mask:0x3 bound_ctrl:1
	v_add_f32_dpp v110, v44, v44 row_mirror row_mask:0xf bank_mask:0xc bound_ctrl:1
	v_add_f32_dpp v12, v12, v12 quad_perm:[2,3,0,1] row_mask:0xf bank_mask:0xf bound_ctrl:1
	v_pk_mul_f32 v[6:7], v[30:31], v[118:119] op_sel:[0,1] op_sel_hi:[1,1]
	v_pk_mul_f32 v[8:9], v[32:33], v[118:119] op_sel:[0,1] op_sel_hi:[1,1]
	v_add_f32_dpp v12, v12, v12 row_half_mirror row_mask:0xf bank_mask:0xf bound_ctrl:1
	v_pk_fma_f32 v[6:7], v[2:3], v[22:23], v[6:7]
	v_pk_fma_f32 v[8:9], v[4:5], v[24:25], v[8:9]
	v_add_f32_dpp v12, v12, v12 row_mirror row_mask:0xf bank_mask:0xf bound_ctrl:1
	ds_read_b128 v[156:159], v84 offset:39744
	ds_read_b128 v[144:147], v84 offset:38976
	ds_read_b128 v[152:155], v84 offset:39488
	ds_read_b128 v[148:151], v84 offset:39232
	ds_read_b128 v[160:163], v84 offset:40000
	v_pk_fma_f32 v[2:3], v[26:27], v[12:13], v[6:7] op_sel_hi:[1,0,1] neg_lo:[0,1,0] neg_hi:[0,1,0]
	v_pk_fma_f32 v[4:5], v[28:29], v[12:13], v[8:9] op_sel_hi:[1,0,1] neg_lo:[0,1,0] neg_hi:[0,1,0]
	s_waitcnt lgkmcnt(5)
	v_pk_mul_f32 v[10:11], v[2:3], v[132:133]
	v_pk_fma_f32 v[10:11], v[4:5], v[134:135], v[10:11]
	v_pk_mul_f32 v[14:15], v[2:3], v[38:39]
	v_add_f32_e32 v12, v10, v11
	v_pk_fma_f32 v[14:15], v[4:5], v[40:41], v[14:15]
	v_add_f32_e64 v44, v14, v15
	v_add_f32_dpp v12, v12, v12 quad_perm:[1,0,3,2] row_mask:0xf bank_mask:0xf bound_ctrl:1
	v_add_f32_dpp v111, v111, v111 row_mirror row_mask:0xf bank_mask:0x3 bound_ctrl:1
	v_add_f32_dpp v111, v44, v44 row_mirror row_mask:0xf bank_mask:0xc bound_ctrl:1
	v_add_f32_dpp v12, v12, v12 quad_perm:[2,3,0,1] row_mask:0xf bank_mask:0xf bound_ctrl:1
	v_pk_mul_f32 v[6:7], v[128:129], v[92:93] op_sel_hi:[1,0]
	v_pk_mul_f32 v[8:9], v[130:131], v[92:93] op_sel_hi:[1,0]
	v_add_f32_dpp v12, v12, v12 row_half_mirror row_mask:0xf bank_mask:0xf bound_ctrl:1
	v_pk_fma_f32 v[6:7], v[2:3], v[120:121], v[6:7]
	v_pk_fma_f32 v[8:9], v[4:5], v[122:123], v[8:9]
	v_add_f32_dpp v12, v12, v12 row_mirror row_mask:0xf bank_mask:0xf bound_ctrl:1
	ds_read_b128 v[180:183], v84 offset:41088
	ds_read_b128 v[168:171], v84 offset:40320
	ds_read_b128 v[176:179], v84 offset:40832
	ds_read_b128 v[172:175], v84 offset:40576
	ds_read_b128 v[184:187], v84 offset:41344
	v_pk_fma_f32 v[2:3], v[124:125], v[12:13], v[6:7] op_sel_hi:[1,0,1] neg_lo:[0,1,0] neg_hi:[0,1,0]
	v_pk_fma_f32 v[4:5], v[126:127], v[12:13], v[8:9] op_sel_hi:[1,0,1] neg_lo:[0,1,0] neg_hi:[0,1,0]
	s_waitcnt lgkmcnt(5)
	v_pk_mul_f32 v[10:11], v[2:3], v[156:157]
	v_pk_fma_f32 v[10:11], v[4:5], v[158:159], v[10:11]
	v_pk_mul_f32 v[14:15], v[2:3], v[136:137]
	v_add_f32_e32 v12, v10, v11
	v_pk_fma_f32 v[14:15], v[4:5], v[138:139], v[14:15]
	v_add_f32_e64 v44, v14, v15
	v_add_f32_dpp v12, v12, v12 quad_perm:[1,0,3,2] row_mask:0xf bank_mask:0xf bound_ctrl:1
	v_add_f32_dpp v112, v112, v112 row_mirror row_mask:0xf bank_mask:0x3 bound_ctrl:1
	v_add_f32_dpp v112, v44, v44 row_mirror row_mask:0xf bank_mask:0xc bound_ctrl:1
	v_add_f32_dpp v12, v12, v12 quad_perm:[2,3,0,1] row_mask:0xf bank_mask:0xf bound_ctrl:1
	v_pk_mul_f32 v[6:7], v[152:153], v[92:93] op_sel:[0,1] op_sel_hi:[1,1]
	v_pk_mul_f32 v[8:9], v[154:155], v[92:93] op_sel:[0,1] op_sel_hi:[1,1]
	v_add_f32_dpp v12, v12, v12 row_half_mirror row_mask:0xf bank_mask:0xf bound_ctrl:1
	v_pk_fma_f32 v[6:7], v[2:3], v[144:145], v[6:7]
	v_pk_fma_f32 v[8:9], v[4:5], v[146:147], v[8:9]
	v_add_f32_dpp v12, v12, v12 row_mirror row_mask:0xf bank_mask:0xf bound_ctrl:1
	ds_read_b128 v[34:37], v84 offset:42432
	ds_read_b128 v[22:25], v84 offset:41664
	ds_read_b128 v[30:33], v84 offset:42176
	ds_read_b128 v[26:29], v84 offset:41920
	ds_read_b128 v[38:41], v84 offset:42688
	v_pk_fma_f32 v[2:3], v[148:149], v[12:13], v[6:7] op_sel_hi:[1,0,1] neg_lo:[0,1,0] neg_hi:[0,1,0]
	v_pk_fma_f32 v[4:5], v[150:151], v[12:13], v[8:9] op_sel_hi:[1,0,1] neg_lo:[0,1,0] neg_hi:[0,1,0]
	s_waitcnt lgkmcnt(5)
; #define LAS __attribute__((address_space(3)))
; template <int CTRL> __device__ __forceinline__ float dpp_f(float v) { return __int_as_float(__builtin_amdgcn_update_dpp(0, __float_as_int(v), CTRL, 0xf, 0xf, true)); }
; __device__ __forceinline__ float row16_sum(float v) { v += dpp_f<0xB1>(v); v += dpp_f<0x4E>(v); v += dpp_f<0x141>(v); v += dpp_f<0x140>(v); return v; }
; __device__ __forceinline__ float tr16_sum(const float (&p)[16], int kq) {
;     const bool b3 = (kq & 8) != 0, b2 = (kq & 4) != 0, b1 = (kq & 2) != 0, b0 = (kq & 1) != 0;
;     float q[8], r[4], u[2];
; #pragma unroll
;     for (int t = 0; t < 8; ++t) { const float keep = b3 ? p[t + 8] : p[t], send = b3 ? p[t] : p[t + 8]; q[t] = keep + dpp_f<0x140>(send); }
; #pragma unroll
;     for (int t = 0; t < 4; ++t) { const float keep = b2 ? q[t + 4] : q[t], send = b2 ? q[t] : q[t + 4]; r[t] = keep + dpp_f<0x141>(send); }
; #pragma unroll
;     for (int t = 0; t < 2; ++t) { const float keep = b1 ? r[t + 2] : r[t], send = b1 ? r[t] : r[t + 2]; u[t] = keep + dpp_f<0x4E>(send); }
;     const float keep = b0 ? u[1] : u[0], send = b0 ? u[0] : u[1];
;     return keep + dpp_f<0xB1>(send);
; __device__ __forceinline__ void rwkv_scan_unit(LAS unsigned char* lds, const float* Wd, const float* V, const bf16_t* RKKB, float* Yraw, int p, int rg, int tid) {
;     ...
;             for (int st = 0; st < SCAN_CH; ++st) {
;                 f32x4 wn = w, bn = b, kn = k, kkn = kk, rn = r; float vn = v;
;                 if (st + 1 < SCAN_CH) { const int o = (st + 1) * SCAN_STEP_B;
;                     wn = *(LAS const f32x4*)(sl + o); bn = *(LAS const f32x4*)(sl + o + 256); kn = *(LAS const f32x4*)(sl + o + 512); kkn = *(LAS const f32x4*)(sl + o + 768); rn = *(LAS const f32x4*)(sl + o + 1024);
;                     vn = *(LAS const float*)(vl + o); }
;                 float sa = (S[0] * kk[0] + S[1] * kk[1]) + (S[2] * kk[2] + S[3] * kk[3]);
;                 const f32x4 kvt = k * v;
;                 sa = -row16_sum(sa);
;                 S = S * w + (b * sa + kvt);
;                 yp[st & 15] = (S[0] * r[0] + S[1] * r[1]) + (S[2] * r[2] + S[3] * r[3]);
;                 if ((st & 15) == 15) yo[(size_t)(st - 15) * 64] = tr16_sum(yp, kq);
;                 w = wn; b = bn; k = kn; kk = kkn; r = rn; v = vn;
;             }
;         }
;         __syncthreads();
;     }
	v_pk_mul_f32 v[10:11], v[2:3], v[180:181]
	v_pk_fma_f32 v[10:11], v[4:5], v[182:183], v[10:11]
	v_pk_mul_f32 v[14:15], v[2:3], v[160:161]
	v_add_f32_e32 v12, v10, v11
	v_pk_fma_f32 v[14:15], v[4:5], v[162:163], v[14:15]
	v_add_f32_e64 v44, v14, v15
	v_add_f32_dpp v12, v12, v12 quad_perm:[1,0,3,2] row_mask:0xf bank_mask:0xf bound_ctrl:1
	v_add_f32_dpp v113, v113, v113 row_mirror row_mask:0xf bank_mask:0x3 bound_ctrl:1
	v_add_f32_dpp v113, v44, v44 row_mirror row_mask:0xf bank_mask:0xc bound_ctrl:1
	v_add_f32_dpp v12, v12, v12 quad_perm:[2,3,0,1] row_mask:0xf bank_mask:0xf bound_ctrl:1
	v_pk_mul_f32 v[6:7], v[176:177], v[94:95] op_sel_hi:[1,0]
	v_pk_mul_f32 v[8:9], v[178:179], v[94:95] op_sel_hi:[1,0]
	v_add_f32_dpp v12, v12, v12 row_half_mirror row_mask:0xf bank_mask:0xf bound_ctrl:1
	v_pk_fma_f32 v[6:7], v[2:3], v[168:169], v[6:7]
	v_pk_fma_f32 v[8:9], v[4:5], v[170:171], v[8:9]
	v_add_f32_dpp v12, v12, v12 row_mirror row_mask:0xf bank_mask:0xf bound_ctrl:1
	ds_read_b128 v[132:135], v86 offset:768
	ds_read_b128 v[120:123], v86
	ds_read_b128 v[128:131], v86 offset:512
	ds_read_b128 v[116:119], v97
	ds_read_b128 v[124:127], v86 offset:256
	ds_read_b128 v[136:139], v86 offset:1024
	v_pk_fma_f32 v[2:3], v[172:173], v[12:13], v[6:7] op_sel_hi:[1,0,1] neg_lo:[0,1,0] neg_hi:[0,1,0]
	v_pk_fma_f32 v[4:5], v[174:175], v[12:13], v[8:9] op_sel_hi:[1,0,1] neg_lo:[0,1,0] neg_hi:[0,1,0]
	s_waitcnt lgkmcnt(6)
	v_pk_mul_f32 v[10:11], v[2:3], v[34:35]
	v_pk_fma_f32 v[10:11], v[4:5], v[36:37], v[10:11]
	v_pk_mul_f32 v[14:15], v[2:3], v[184:185]
	v_add_f32_e32 v12, v10, v11
	v_pk_fma_f32 v[14:15], v[4:5], v[186:187], v[14:15]
	v_add_f32_e64 v44, v14, v15
	v_add_f32_dpp v12, v12, v12 quad_perm:[1,0,3,2] row_mask:0xf bank_mask:0xf bound_ctrl:1
	v_add_f32_dpp v114, v114, v114 row_mirror row_mask:0xf bank_mask:0x3 bound_ctrl:1
	v_add_f32_dpp v114, v44, v44 row_mirror row_mask:0xf bank_mask:0xc bound_ctrl:1
	v_add_f32_dpp v12, v12, v12 quad_perm:[2,3,0,1] row_mask:0xf bank_mask:0xf bound_ctrl:1
	v_pk_mul_f32 v[6:7], v[30:31], v[94:95] op_sel:[0,1] op_sel_hi:[1,1]
	v_pk_mul_f32 v[8:9], v[32:33], v[94:95] op_sel:[0,1] op_sel_hi:[1,1]
	v_add_f32_dpp v12, v12, v12 row_half_mirror row_mask:0xf bank_mask:0xf bound_ctrl:1
	v_pk_fma_f32 v[6:7], v[2:3], v[22:23], v[6:7]
	v_pk_fma_f32 v[8:9], v[4:5], v[24:25], v[8:9]
	v_add_f32_dpp v12, v12, v12 row_mirror row_mask:0xf bank_mask:0xf bound_ctrl:1
	ds_read_b128 v[156:159], v86 offset:2112
	ds_read_b128 v[144:147], v86 offset:1344
	ds_read_b128 v[152:155], v86 offset:1856
	ds_read_b128 v[148:151], v86 offset:1600
	ds_read_b128 v[160:163], v86 offset:2368
	v_pk_fma_f32 v[2:3], v[26:27], v[12:13], v[6:7] op_sel_hi:[1,0,1] neg_lo:[0,1,0] neg_hi:[0,1,0]
	v_pk_fma_f32 v[4:5], v[28:29], v[12:13], v[8:9] op_sel_hi:[1,0,1] neg_lo:[0,1,0] neg_hi:[0,1,0]
	v_pk_mul_f32 v[14:15], v[2:3], v[38:39]
	v_pk_fma_f32 v[14:15], v[4:5], v[40:41], v[14:15]
	v_add_f32_e64 v44, v14, v15
	v_add_f32_dpp v115, v115, v115 row_mirror row_mask:0xf bank_mask:0x3 bound_ctrl:1
	s_nop 0
	v_add_f32_dpp v115, v44, v44 row_mirror row_mask:0xf bank_mask:0xc bound_ctrl:1
	v_add_f32_dpp v108, v108, v108 row_half_mirror row_mask:0xf bank_mask:0x5 bound_ctrl:1
	v_add_f32_dpp v108, v112, v112 row_half_mirror row_mask:0xf bank_mask:0xa bound_ctrl:1
	v_add_f32_dpp v109, v109, v109 row_half_mirror row_mask:0xf bank_mask:0x5 bound_ctrl:1
	v_add_f32_dpp v109, v113, v113 row_half_mirror row_mask:0xf bank_mask:0xa bound_ctrl:1
	v_add_f32_dpp v110, v110, v110 row_half_mirror row_mask:0xf bank_mask:0x5 bound_ctrl:1
	v_add_f32_dpp v110, v114, v114 row_half_mirror row_mask:0xf bank_mask:0xa bound_ctrl:1
	v_add_f32_dpp v111, v111, v111 row_half_mirror row_mask:0xf bank_mask:0x5 bound_ctrl:1
	v_add_f32_dpp v111, v115, v115 row_half_mirror row_mask:0xf bank_mask:0xa bound_ctrl:1
	v_cndmask_b32_e64 v16, v110, v108, s[8:9]
	v_cndmask_b32_e64 v17, v108, v110, s[8:9]
	s_nop 1
	v_add_f32_dpp v16, v17, v16 quad_perm:[2,3,0,1] row_mask:0xf bank_mask:0xf bound_ctrl:1
	v_cndmask_b32_e64 v18, v111, v109, s[8:9]
	v_cndmask_b32_e64 v19, v109, v111, s[8:9]
	s_nop 1
	v_add_f32_dpp v18, v19, v18 quad_perm:[2,3,0,1] row_mask:0xf bank_mask:0xf bound_ctrl:1
	v_cndmask_b32_e64 v17, v18, v16, s[10:11]
	v_cndmask_b32_e64 v19, v16, v18, s[10:11]
	s_nop 1
	v_add_f32_dpp v17, v19, v17 quad_perm:[1,0,3,2] row_mask:0xf bank_mask:0xf bound_ctrl:1
	global_store_dword v[90:91], v17, off
	s_add_i32 s22, s22, 1
	s_mov_b64 s[18:19], 0x2000
	v_lshl_add_u64 v[60:61], v[60:61], 0, s[18:19]
	s_mov_b64 s[68:69], 0x2000
	s_cmpk_eq_i32 s22, 0x80
	s_barrier
	s_cbranch_scc1 .LBB0_370
	s_branch .Lscan_top
